# mix2 LRU pass-1: loads of all 16 unrolled steps hoisted to loop top with counted waits; LRU items moved to the idle upper half of threads
# speedup vs baseline: 1.0870x; 1.0099x over previous
.LBB0_371:
	s_or_b64 exec, exec, s[14:15]
	s_mov_b32 s0, 0x10000
	v_subrev_u32_e32 v177, s0, v177
	v_cmp_gt_u32_e32 vcc, s0, v177
	s_and_saveexec_b64 s[4:5], vcc
	s_cbranch_execz .LBB0_376
	v_readlane_b32 s0, v254, 11
	v_readlane_b32 s1, v254, 12
	s_add_u32 s6, s0, 0x26db5000
	s_addc_u32 s7, s1, 0
	v_readlane_b32 s0, v254, 9
	v_lshlrev_b32_e32 v22, 2, v177
	s_lshl_b32 s12, s0, 10
	s_mov_b64 s[8:9], 0
	v_readlane_b32 s1, v254, 10

.LBB0_374:
	v_lshl_add_u64 v[34:35], v[10:11], 0, s[10:11]
	v_add_co_u32_e32 v36, vcc, 0x22cb5000, v34
	s_nop 1
	v_addc_co_u32_e32 v37, vcc, 0, v35, vcc
	v_add_co_u32_e32 v38, vcc, s13, v34
	global_load_dwordx2 v[40:41], v[36:37], off
	s_nop 0
	v_addc_co_u32_e32 v39, vcc, 0, v35, vcc
	v_add_co_u32_e32 v42, vcc, s15, v34
	s_nop 1
	v_addc_co_u32_e32 v43, vcc, 0, v35, vcc
	global_load_dwordx2 v[44:45], v[42:43], off offset:-4096
	global_load_dwordx2 v[46:47], v[36:37], off offset:2048
	global_load_dwordx2 v[48:49], v[38:39], off offset:2048
	v_add_co_u32_e32 v50, vcc, s14, v34
	s_nop 1
	v_addc_co_u32_e32 v51, vcc, 0, v35, vcc
	v_add_co_u32_e32 v52, vcc, s34, v34
	s_nop 1
	v_addc_co_u32_e32 v53, vcc, 0, v35, vcc
	global_load_dwordx2 v[54:55], v[52:53], off offset:-4096
	global_load_dwordx2 v[56:57], v[42:43], off
	global_load_dwordx2 v[58:59], v[50:51], off offset:2048
	global_load_dwordx2 v[60:61], v[42:43], off offset:2048
	v_add_co_u32_e32 v38, vcc, s35, v34
	s_nop 1
	v_addc_co_u32_e32 v39, vcc, 0, v35, vcc
	v_add_co_u32_e32 v62, vcc, s37, v34
	global_load_dwordx2 v[64:65], v[52:53], off
	s_nop 0
	v_addc_co_u32_e32 v63, vcc, 0, v35, vcc
	global_load_dwordx2 v[66:67], v[62:63], off offset:-4096
	global_load_dwordx2 v[68:69], v[52:53], off offset:2048
	global_load_dwordx2 v[70:71], v[38:39], off offset:2048
	s_mov_b32 s98, 0x22cb9000
	v_add_co_u32_e32 v36, vcc, s36, v34
	s_nop 1
	v_addc_co_u32_e32 v37, vcc, 0, v35, vcc
	v_add_co_u32_e32 v50, vcc, s98, v34
	s_nop 1
	v_addc_co_u32_e32 v51, vcc, 0, v35, vcc
	global_load_dwordx2 v[72:73], v[50:51], off offset:-4096
	global_load_dwordx2 v[74:75], v[62:63], off
	global_load_dwordx2 v[76:77], v[36:37], off offset:2048
	global_load_dwordx2 v[78:79], v[62:63], off offset:2048
	s_mov_b32 s98, 0x24d39000
	v_add_co_u32_e32 v38, vcc, s98, v34
	s_mov_b32 s98, 0x24d3a000
	s_nop 0
	v_addc_co_u32_e32 v39, vcc, 0, v35, vcc
	v_add_co_u32_e32 v62, vcc, s98, v34
	global_load_dwordx2 v[80:81], v[50:51], off
	s_nop 0
	v_addc_co_u32_e32 v63, vcc, 0, v35, vcc
	global_load_dwordx2 v[82:83], v[62:63], off offset:-4096
	global_load_dwordx2 v[84:85], v[50:51], off offset:2048
	global_load_dwordx2 v[86:87], v[38:39], off offset:2048
	s_mov_b32 s98, 0x22cba000
	v_add_co_u32_e32 v50, vcc, s98, v34
	s_mov_b32 s98, 0x22cbb000
	s_nop 0
	v_addc_co_u32_e32 v51, vcc, 0, v35, vcc
	v_add_co_u32_e32 v52, vcc, s98, v34
	s_nop 1
	v_addc_co_u32_e32 v53, vcc, 0, v35, vcc
	global_load_dwordx2 v[88:89], v[52:53], off offset:-4096
	global_load_dwordx2 v[90:91], v[62:63], off
	global_load_dwordx2 v[92:93], v[50:51], off offset:2048
	global_load_dwordx2 v[94:95], v[62:63], off offset:2048
	s_mov_b32 s98, 0x24d3b000
	v_add_co_u32_e32 v38, vcc, s98, v34
	s_mov_b32 s98, 0x24d3c000
	s_nop 0
	v_addc_co_u32_e32 v39, vcc, 0, v35, vcc
	v_add_co_u32_e32 v62, vcc, s98, v34
	global_load_dwordx2 v[100:101], v[52:53], off
	s_nop 0
	v_addc_co_u32_e32 v63, vcc, 0, v35, vcc
	global_load_dwordx2 v[102:103], v[62:63], off offset:-4096
	global_load_dwordx2 v[104:105], v[52:53], off offset:2048
	global_load_dwordx2 v[106:107], v[38:39], off offset:2048
	s_mov_b32 s98, 0x22cbc000
	v_add_co_u32_e32 v34, vcc, s98, v34
	s_nop 1
	v_addc_co_u32_e32 v35, vcc, 0, v35, vcc
	global_load_dwordx2 v[108:109], v[34:35], off
	global_load_dwordx2 v[110:111], v[62:63], off
	global_load_dwordx2 v[112:113], v[34:35], off offset:2048
	global_load_dwordx2 v[114:115], v[62:63], off offset:2048
	v_lshl_add_u64 v[12:13], v[10:11], 0, s[10:11]
	v_add_co_u32_e32 v16, vcc, 0x22cb5000, v12
	s_add_u32 s10, s10, 0x8000
	s_nop 0
	v_addc_co_u32_e32 v17, vcc, 0, v13, vcc
	v_add_co_u32_e32 v20, vcc, s13, v12
	s_waitcnt vmcnt(31)
	v_mov_b32_e32 v18, v40
	v_mov_b32_e32 v19, v41
	s_nop 0
	v_addc_co_u32_e32 v21, vcc, 0, v13, vcc
	v_add_co_u32_e32 v14, vcc, s15, v12
	s_addc_u32 s11, s11, 0
	s_nop 0
	v_addc_co_u32_e32 v15, vcc, 0, v13, vcc
	s_waitcnt vmcnt(30)
	v_mov_b32_e32 v24, v44
	v_mov_b32_e32 v25, v45
	s_cmp_eq_u32 s10, 0x20000
	s_nop 0
	v_lshlrev_b32_e32 v28, 16, v18
	v_and_b32_e32 v9, 0xffff0000, v18
	v_mul_f32_e32 v9, 0x3fb8aa3b, v9
	v_and_b32_e32 v32, 0xffff0000, v19
	v_lshlrev_b32_e32 v19, 16, v19
	s_nop 0
	v_and_b32_e32 v27, 0xffff0000, v24
	v_lshlrev_b32_e32 v26, 16, v24
	v_mul_f32_e32 v24, 0x3fb8aa3b, v28
	v_exp_f32_e32 v28, v24
	v_lshlrev_b32_e32 v18, 16, v25
	v_fma_f32 v24, -v28, v28, 1.0
	v_max_f32_e32 v24, 0, v24
	v_cmp_gt_f32_e32 vcc, s97, v24
	v_mul_f32_e32 v29, 0x4f800000, v24
	s_nop 0
	v_cndmask_b32_e32 v24, v24, v29, vcc
	v_sqrt_f32_e32 v29, v24
	s_nop 0
	v_add_u32_e32 v30, -1, v29
	v_fma_f32 v31, -v30, v29, v24
	v_cmp_ge_f32_e64 s[0:1], 0, v31
	v_add_u32_e32 v31, 1, v29
	s_nop 0
	v_cndmask_b32_e64 v30, v29, v30, s[0:1]
	v_fma_f32 v29, -v31, v29, v24
	v_cmp_lt_f32_e64 s[0:1], 0, v29
	s_nop 1
	v_cndmask_b32_e64 v29, v30, v31, s[0:1]
	v_mul_f32_e32 v30, 0x37800000, v29
	v_cndmask_b32_e32 v29, v29, v30, vcc
	v_cmp_class_f32_e32 vcc, v24, v149
	s_nop 1
	v_cndmask_b32_e32 v30, v29, v24, vcc
	v_exp_f32_e32 v29, v9
	s_nop 0
	v_fma_f32 v9, -v29, v29, 1.0
	v_max_f32_e32 v9, 0, v9
	v_cmp_gt_f32_e32 vcc, s97, v9
	v_mul_f32_e32 v24, 0x4f800000, v9
	v_pk_mul_f32 v[4:5], v[4:5], v[28:29]
	v_cndmask_b32_e32 v9, v9, v24, vcc
	v_sqrt_f32_e32 v24, v9
	s_nop 0
	v_add_u32_e32 v31, -1, v24
	v_fma_f32 v33, -v31, v24, v9
	v_cmp_ge_f32_e64 s[0:1], 0, v33
	v_add_u32_e32 v33, 1, v24
	s_nop 0
	v_cndmask_b32_e64 v31, v24, v31, s[0:1]
	v_fma_f32 v24, -v33, v24, v9
	v_cmp_lt_f32_e64 s[0:1], 0, v24
	s_nop 1
	v_cndmask_b32_e64 v24, v31, v33, s[0:1]
	v_mul_f32_e32 v31, 0x37800000, v24
	v_cndmask_b32_e32 v24, v24, v31, vcc
	v_cmp_class_f32_e32 vcc, v9, v149
	s_nop 1
	v_cndmask_b32_e32 v31, v24, v9, vcc
	v_pk_mul_f32 v[26:27], v[30:31], v[26:27]
	v_mul_f32_e32 v9, 0x3fb8aa3b, v19
	v_pk_fma_f32 v[0:1], v[0:1], v[28:29], v[26:27]
	v_exp_f32_e32 v26, v9
	s_nop 0
	v_fma_f32 v9, -v26, v26, 1.0
	v_max_f32_e32 v9, 0, v9
	v_cmp_gt_f32_e32 vcc, s97, v9
	v_mul_f32_e32 v19, 0x4f800000, v9
	s_nop 0
	v_cndmask_b32_e32 v9, v9, v19, vcc
	v_sqrt_f32_e32 v19, v9
	s_nop 0
	v_add_u32_e32 v24, -1, v19
	v_fma_f32 v27, -v24, v19, v9
	v_cmp_ge_f32_e64 s[0:1], 0, v27
	v_add_u32_e32 v27, 1, v19
	s_nop 0
	v_cndmask_b32_e64 v24, v19, v24, s[0:1]
	v_fma_f32 v19, -v27, v19, v9
	v_cmp_lt_f32_e64 s[0:1], 0, v19
	s_nop 1
	v_cndmask_b32_e64 v19, v24, v27, s[0:1]
	v_mul_f32_e32 v24, 0x37800000, v19
	v_cndmask_b32_e32 v19, v19, v24, vcc
	v_cmp_class_f32_e32 vcc, v9, v149
	s_nop 1
	v_cndmask_b32_e32 v24, v19, v9, vcc
	v_mul_f32_e32 v9, 0x3fb8aa3b, v32
	v_exp_f32_e32 v27, v9
	v_and_b32_e32 v19, 0xffff0000, v25
	v_fma_f32 v9, -v27, v27, 1.0
	v_max_f32_e32 v9, 0, v9
	v_cmp_gt_f32_e32 vcc, s97, v9
	v_mul_f32_e32 v25, 0x4f800000, v9
	v_pk_mul_f32 v[6:7], v[6:7], v[26:27]
	v_cndmask_b32_e32 v9, v9, v25, vcc
	v_sqrt_f32_e32 v25, v9
	s_nop 0
	v_add_u32_e32 v28, -1, v25
	v_fma_f32 v29, -v28, v25, v9
	v_cmp_ge_f32_e64 s[0:1], 0, v29
	v_add_u32_e32 v29, 1, v25
	s_nop 0
	v_cndmask_b32_e64 v28, v25, v28, s[0:1]
	v_fma_f32 v25, -v29, v25, v9
	v_cmp_lt_f32_e64 s[0:1], 0, v25
	s_nop 1
	v_cndmask_b32_e64 v25, v28, v29, s[0:1]
	v_mul_f32_e32 v28, 0x37800000, v25
	v_cndmask_b32_e32 v25, v25, v28, vcc
	v_cmp_class_f32_e32 vcc, v9, v149
	s_nop 1
	v_cndmask_b32_e32 v25, v25, v9, vcc
	v_pk_mul_f32 v[18:19], v[24:25], v[18:19]
	s_nop 0
	v_pk_fma_f32 v[2:3], v[2:3], v[26:27], v[18:19]
	s_waitcnt vmcnt(29)
	v_mov_b32_e32 v16, v46
	v_mov_b32_e32 v17, v47
	s_nop 0
	s_waitcnt vmcnt(28)
	v_mov_b32_e32 v18, v48
	v_mov_b32_e32 v19, v49
	s_nop 0
	v_lshlrev_b32_e32 v24, 16, v16
	s_nop 0
	v_and_b32_e32 v21, 0xffff0000, v18
	v_lshlrev_b32_e32 v20, 16, v18
	v_mul_f32_e32 v18, 0x3fb8aa3b, v24
	v_exp_f32_e32 v24, v18
	v_and_b32_e32 v9, 0xffff0000, v16
	v_mul_f32_e32 v9, 0x3fb8aa3b, v9
	v_and_b32_e32 v28, 0xffff0000, v17
	v_fma_f32 v18, -v24, v24, 1.0
	v_max_f32_e32 v18, 0, v18
	v_cmp_gt_f32_e32 vcc, s97, v18
	v_mul_f32_e32 v25, 0x4f800000, v18
	v_lshlrev_b32_e32 v17, 16, v17
	v_cndmask_b32_e32 v18, v18, v25, vcc
	v_sqrt_f32_e32 v25, v18
	v_lshlrev_b32_e32 v16, 16, v19
	v_add_u32_e32 v26, -1, v25
	v_fma_f32 v27, -v26, v25, v18
	v_cmp_ge_f32_e64 s[0:1], 0, v27
	v_add_u32_e32 v27, 1, v25
	s_nop 0
	v_cndmask_b32_e64 v26, v25, v26, s[0:1]
	v_fma_f32 v25, -v27, v25, v18
	v_cmp_lt_f32_e64 s[0:1], 0, v25
	s_nop 1
	v_cndmask_b32_e64 v25, v26, v27, s[0:1]
	v_mul_f32_e32 v26, 0x37800000, v25
	v_cndmask_b32_e32 v25, v25, v26, vcc
	v_cmp_class_f32_e32 vcc, v18, v149
	s_nop 1
	v_cndmask_b32_e32 v26, v25, v18, vcc
	v_exp_f32_e32 v25, v9
	s_nop 0
	v_fma_f32 v9, -v25, v25, 1.0
	v_max_f32_e32 v9, 0, v9
	v_cmp_gt_f32_e32 vcc, s97, v9
	v_mul_f32_e32 v18, 0x4f800000, v9
	v_pk_mul_f32 v[4:5], v[4:5], v[24:25]
	v_cndmask_b32_e32 v9, v9, v18, vcc
	v_sqrt_f32_e32 v18, v9
	s_nop 0
	v_add_u32_e32 v27, -1, v18
	v_fma_f32 v29, -v27, v18, v9
	v_cmp_ge_f32_e64 s[0:1], 0, v29
	v_add_u32_e32 v29, 1, v18
	s_nop 0
	v_cndmask_b32_e64 v27, v18, v27, s[0:1]
	v_fma_f32 v18, -v29, v18, v9
	v_cmp_lt_f32_e64 s[0:1], 0, v18
	s_nop 1
	v_cndmask_b32_e64 v18, v27, v29, s[0:1]
	v_mul_f32_e32 v27, 0x37800000, v18
	v_cndmask_b32_e32 v18, v18, v27, vcc
	v_cmp_class_f32_e32 vcc, v9, v149
	s_nop 1
	v_cndmask_b32_e32 v27, v18, v9, vcc
	v_pk_mul_f32 v[20:21], v[26:27], v[20:21]
	v_mul_f32_e32 v9, 0x3fb8aa3b, v17
	v_pk_fma_f32 v[0:1], v[0:1], v[24:25], v[20:21]
	v_exp_f32_e32 v20, v9
	s_nop 0
	v_fma_f32 v9, -v20, v20, 1.0
	v_max_f32_e32 v9, 0, v9
	v_cmp_gt_f32_e32 vcc, s97, v9
	v_mul_f32_e32 v17, 0x4f800000, v9
	s_nop 0
	v_cndmask_b32_e32 v9, v9, v17, vcc
	v_sqrt_f32_e32 v17, v9
	s_nop 0
	v_add_u32_e32 v18, -1, v17
	v_fma_f32 v21, -v18, v17, v9
	v_cmp_ge_f32_e64 s[0:1], 0, v21
	v_add_u32_e32 v21, 1, v17
	s_nop 0
	v_cndmask_b32_e64 v18, v17, v18, s[0:1]
	v_fma_f32 v17, -v21, v17, v9
	v_cmp_lt_f32_e64 s[0:1], 0, v17
	s_nop 1
	v_cndmask_b32_e64 v17, v18, v21, s[0:1]
	v_mul_f32_e32 v18, 0x37800000, v17
	v_cndmask_b32_e32 v17, v17, v18, vcc
	v_cmp_class_f32_e32 vcc, v9, v149
	s_nop 1
	v_cndmask_b32_e32 v18, v17, v9, vcc
	v_mul_f32_e32 v9, 0x3fb8aa3b, v28
	v_exp_f32_e32 v21, v9
	v_and_b32_e32 v17, 0xffff0000, v19
	v_fma_f32 v9, -v21, v21, 1.0
	v_max_f32_e32 v9, 0, v9
	v_cmp_gt_f32_e32 vcc, s97, v9
	v_mul_f32_e32 v19, 0x4f800000, v9
	v_pk_mul_f32 v[6:7], v[6:7], v[20:21]
	v_cndmask_b32_e32 v9, v9, v19, vcc
	v_sqrt_f32_e32 v19, v9
	s_nop 0
	v_add_u32_e32 v24, -1, v19
	v_fma_f32 v25, -v24, v19, v9
	v_cmp_ge_f32_e64 s[0:1], 0, v25
	v_add_u32_e32 v25, 1, v19
	s_nop 0
	v_cndmask_b32_e64 v24, v19, v24, s[0:1]
	v_fma_f32 v19, -v25, v19, v9
	v_cmp_lt_f32_e64 s[0:1], 0, v19
	s_nop 1
	v_cndmask_b32_e64 v19, v24, v25, s[0:1]
	v_mul_f32_e32 v24, 0x37800000, v19
	v_cndmask_b32_e32 v19, v19, v24, vcc
	v_cmp_class_f32_e32 vcc, v9, v149
	s_nop 1
	v_cndmask_b32_e32 v19, v19, v9, vcc
	v_pk_mul_f32 v[16:17], v[18:19], v[16:17]
	v_add_co_u32_e32 v18, vcc, s14, v12
	v_pk_fma_f32 v[16:17], v[2:3], v[20:21], v[16:17]
	s_nop 0
	v_addc_co_u32_e32 v19, vcc, 0, v13, vcc
	v_add_co_u32_e32 v2, vcc, s34, v12
	s_nop 1
	v_addc_co_u32_e32 v3, vcc, 0, v13, vcc
	s_waitcnt vmcnt(27)
	v_mov_b32_e32 v20, v54
	v_mov_b32_e32 v21, v55
	s_waitcnt vmcnt(26)
	v_mov_b32_e32 v24, v56
	v_mov_b32_e32 v25, v57
	s_nop 0
	s_waitcnt vmcnt(25)
	v_mov_b32_e32 v18, v58
	v_mov_b32_e32 v19, v59
	s_nop 0
	s_waitcnt vmcnt(24)
	v_mov_b32_e32 v14, v60
	v_mov_b32_e32 v15, v61
	s_nop 0
	v_lshlrev_b32_e32 v28, 16, v20
	s_nop 0
	v_and_b32_e32 v27, 0xffff0000, v24
	v_lshlrev_b32_e32 v26, 16, v24
	v_mul_f32_e32 v24, 0x3fb8aa3b, v28
	v_exp_f32_e32 v28, v24
	v_and_b32_e32 v9, 0xffff0000, v20
	v_mul_f32_e32 v9, 0x3fb8aa3b, v9
	v_and_b32_e32 v32, 0xffff0000, v21
	v_fma_f32 v24, -v28, v28, 1.0
	v_max_f32_e32 v24, 0, v24
	v_cmp_gt_f32_e32 vcc, s97, v24
	v_mul_f32_e32 v29, 0x4f800000, v24
	v_lshlrev_b32_e32 v21, 16, v21
	v_cndmask_b32_e32 v24, v24, v29, vcc
	v_sqrt_f32_e32 v29, v24
	v_lshlrev_b32_e32 v20, 16, v25
	v_add_u32_e32 v30, -1, v29
	v_fma_f32 v31, -v30, v29, v24
	v_cmp_ge_f32_e64 s[0:1], 0, v31
	v_add_u32_e32 v31, 1, v29
	s_nop 0
	v_cndmask_b32_e64 v30, v29, v30, s[0:1]
	v_fma_f32 v29, -v31, v29, v24
	v_cmp_lt_f32_e64 s[0:1], 0, v29
	s_nop 1
	v_cndmask_b32_e64 v29, v30, v31, s[0:1]
	v_mul_f32_e32 v30, 0x37800000, v29
	v_cndmask_b32_e32 v29, v29, v30, vcc
	v_cmp_class_f32_e32 vcc, v24, v149
	s_nop 1
	v_cndmask_b32_e32 v30, v29, v24, vcc
	v_exp_f32_e32 v29, v9
	s_nop 0
	v_fma_f32 v9, -v29, v29, 1.0
	v_max_f32_e32 v9, 0, v9
	v_cmp_gt_f32_e32 vcc, s97, v9
	v_mul_f32_e32 v24, 0x4f800000, v9
	v_pk_mul_f32 v[4:5], v[4:5], v[28:29]
	v_cndmask_b32_e32 v9, v9, v24, vcc
	v_sqrt_f32_e32 v24, v9
	s_nop 0
	v_add_u32_e32 v31, -1, v24
	v_fma_f32 v33, -v31, v24, v9
	v_cmp_ge_f32_e64 s[0:1], 0, v33
	v_add_u32_e32 v33, 1, v24
	s_nop 0
	v_cndmask_b32_e64 v31, v24, v31, s[0:1]
	v_fma_f32 v24, -v33, v24, v9
	v_cmp_lt_f32_e64 s[0:1], 0, v24
	s_nop 1
	v_cndmask_b32_e64 v24, v31, v33, s[0:1]
	v_mul_f32_e32 v31, 0x37800000, v24
	v_cndmask_b32_e32 v24, v24, v31, vcc
	v_cmp_class_f32_e32 vcc, v9, v149
	s_nop 1
	v_cndmask_b32_e32 v31, v24, v9, vcc
	v_pk_mul_f32 v[26:27], v[30:31], v[26:27]
	v_mul_f32_e32 v9, 0x3fb8aa3b, v21
	v_pk_fma_f32 v[0:1], v[0:1], v[28:29], v[26:27]
	v_exp_f32_e32 v26, v9
	s_nop 0
	v_fma_f32 v9, -v26, v26, 1.0
	v_max_f32_e32 v9, 0, v9
	v_cmp_gt_f32_e32 vcc, s97, v9
	v_mul_f32_e32 v21, 0x4f800000, v9
	s_nop 0
	v_cndmask_b32_e32 v9, v9, v21, vcc
	v_sqrt_f32_e32 v21, v9
	s_nop 0
	v_add_u32_e32 v24, -1, v21
	v_fma_f32 v27, -v24, v21, v9
	v_cmp_ge_f32_e64 s[0:1], 0, v27
	v_add_u32_e32 v27, 1, v21
	s_nop 0
	v_cndmask_b32_e64 v24, v21, v24, s[0:1]
	v_fma_f32 v21, -v27, v21, v9
	v_cmp_lt_f32_e64 s[0:1], 0, v21
	s_nop 1
	v_cndmask_b32_e64 v21, v24, v27, s[0:1]
	v_mul_f32_e32 v24, 0x37800000, v21
	v_cndmask_b32_e32 v21, v21, v24, vcc
	v_cmp_class_f32_e32 vcc, v9, v149
	s_nop 1
	v_cndmask_b32_e32 v24, v21, v9, vcc
	v_mul_f32_e32 v9, 0x3fb8aa3b, v32
	v_exp_f32_e32 v27, v9
	v_and_b32_e32 v21, 0xffff0000, v25
	v_fma_f32 v9, -v27, v27, 1.0
	v_max_f32_e32 v9, 0, v9
	v_cmp_gt_f32_e32 vcc, s97, v9
	v_mul_f32_e32 v25, 0x4f800000, v9
	v_pk_mul_f32 v[6:7], v[6:7], v[26:27]
	v_cndmask_b32_e32 v9, v9, v25, vcc
	v_sqrt_f32_e32 v25, v9
	s_nop 0
	v_add_u32_e32 v28, -1, v25
	v_fma_f32 v29, -v28, v25, v9
	v_cmp_ge_f32_e64 s[0:1], 0, v29
	v_add_u32_e32 v29, 1, v25
	s_nop 0
	v_cndmask_b32_e64 v28, v25, v28, s[0:1]
	v_fma_f32 v25, -v29, v25, v9
	v_cmp_lt_f32_e64 s[0:1], 0, v25
	s_nop 1
	v_cndmask_b32_e64 v25, v28, v29, s[0:1]
	v_mul_f32_e32 v28, 0x37800000, v25
	v_cndmask_b32_e32 v25, v25, v28, vcc
	v_cmp_class_f32_e32 vcc, v9, v149
	s_nop 1
	v_cndmask_b32_e32 v25, v25, v9, vcc
	s_nop 0
	v_and_b32_e32 v9, 0xffff0000, v18
	v_lshlrev_b32_e32 v18, 16, v18
	v_mul_f32_e32 v18, 0x3fb8aa3b, v18
	v_exp_f32_e32 v18, v18
	v_pk_mul_f32 v[20:21], v[24:25], v[20:21]
	v_mul_f32_e32 v9, 0x3fb8aa3b, v9
	v_pk_fma_f32 v[16:17], v[16:17], v[26:27], v[20:21]
	v_and_b32_e32 v26, 0xffff0000, v19
	v_lshlrev_b32_e32 v27, 16, v19
	v_fma_f32 v19, -v18, v18, 1.0
	v_max_f32_e32 v19, 0, v19
	v_cmp_gt_f32_e32 vcc, s97, v19
	v_mul_f32_e32 v24, 0x4f800000, v19
	s_nop 0
	v_and_b32_e32 v21, 0xffff0000, v14
	v_cndmask_b32_e32 v19, v19, v24, vcc
	v_sqrt_f32_e32 v24, v19
	v_lshlrev_b32_e32 v20, 16, v14
	v_lshlrev_b32_e32 v14, 16, v15
	v_and_b32_e32 v15, 0xffff0000, v15
	v_add_u32_e32 v25, -1, v24
	v_fma_f32 v28, -v25, v24, v19
	v_cmp_ge_f32_e64 s[0:1], 0, v28
	v_add_u32_e32 v28, 1, v24
	s_nop 0
	v_cndmask_b32_e64 v25, v24, v25, s[0:1]
	v_fma_f32 v24, -v28, v24, v19
	v_cmp_lt_f32_e64 s[0:1], 0, v24
	s_nop 1
	v_cndmask_b32_e64 v24, v25, v28, s[0:1]
	v_mul_f32_e32 v25, 0x37800000, v24
	v_cndmask_b32_e32 v24, v24, v25, vcc
	v_cmp_class_f32_e32 vcc, v19, v149
	s_nop 1
	v_cndmask_b32_e32 v24, v24, v19, vcc
	v_exp_f32_e32 v19, v9
	s_nop 0
	v_fma_f32 v9, -v19, v19, 1.0
	v_max_f32_e32 v9, 0, v9
	v_cmp_gt_f32_e32 vcc, s97, v9
	v_mul_f32_e32 v25, 0x4f800000, v9
	v_pk_mul_f32 v[4:5], v[4:5], v[18:19]
	v_cndmask_b32_e32 v9, v9, v25, vcc
	v_sqrt_f32_e32 v25, v9
	s_nop 0
	v_add_u32_e32 v28, -1, v25
	v_fma_f32 v29, -v28, v25, v9
	v_cmp_ge_f32_e64 s[0:1], 0, v29
	v_add_u32_e32 v29, 1, v25
	s_nop 0
	v_cndmask_b32_e64 v28, v25, v28, s[0:1]
	v_fma_f32 v25, -v29, v25, v9
	v_cmp_lt_f32_e64 s[0:1], 0, v25
	s_nop 1
	v_cndmask_b32_e64 v25, v28, v29, s[0:1]
	v_mul_f32_e32 v28, 0x37800000, v25
	v_cndmask_b32_e32 v25, v25, v28, vcc
	v_cmp_class_f32_e32 vcc, v9, v149
	s_nop 1
	v_cndmask_b32_e32 v25, v25, v9, vcc
	v_pk_mul_f32 v[20:21], v[24:25], v[20:21]
	s_nop 0
	v_pk_fma_f32 v[18:19], v[0:1], v[18:19], v[20:21]
	v_mul_f32_e32 v0, 0x3fb8aa3b, v27
	v_exp_f32_e32 v0, v0
	s_nop 0
	v_fma_f32 v1, -v0, v0, 1.0
	v_max_f32_e32 v1, 0, v1
	v_cmp_gt_f32_e32 vcc, s97, v1
	v_mul_f32_e32 v9, 0x4f800000, v1
	s_nop 0
	v_cndmask_b32_e32 v1, v1, v9, vcc
	v_sqrt_f32_e32 v9, v1
	s_nop 0
	v_add_u32_e32 v20, -1, v9
	v_fma_f32 v21, -v20, v9, v1
	v_cmp_ge_f32_e64 s[0:1], 0, v21
	v_add_u32_e32 v21, 1, v9
	s_nop 0
	v_cndmask_b32_e64 v20, v9, v20, s[0:1]
	v_fma_f32 v9, -v21, v9, v1
	v_cmp_lt_f32_e64 s[0:1], 0, v9
	s_nop 1
	v_cndmask_b32_e64 v9, v20, v21, s[0:1]
	v_mul_f32_e32 v20, 0x37800000, v9
	v_cndmask_b32_e32 v9, v9, v20, vcc
	v_cmp_class_f32_e32 vcc, v1, v149
	s_nop 1
	v_cndmask_b32_e32 v20, v9, v1, vcc
	v_mul_f32_e32 v1, 0x3fb8aa3b, v26
	v_exp_f32_e32 v1, v1
	s_nop 0
	v_fma_f32 v9, -v1, v1, 1.0
	v_max_f32_e32 v9, 0, v9
	v_cmp_gt_f32_e32 vcc, s97, v9
	v_mul_f32_e32 v21, 0x4f800000, v9
	v_pk_mul_f32 v[6:7], v[6:7], v[0:1]
	v_cndmask_b32_e32 v9, v9, v21, vcc
	v_sqrt_f32_e32 v21, v9
	s_nop 0
	v_add_u32_e32 v24, -1, v21
	v_fma_f32 v25, -v24, v21, v9
	v_cmp_ge_f32_e64 s[0:1], 0, v25
	v_add_u32_e32 v25, 1, v21
	s_nop 0
	v_cndmask_b32_e64 v24, v21, v24, s[0:1]
	v_fma_f32 v21, -v25, v21, v9
	v_cmp_lt_f32_e64 s[0:1], 0, v21
	s_nop 1
	v_cndmask_b32_e64 v21, v24, v25, s[0:1]
	v_mul_f32_e32 v24, 0x37800000, v21
	v_cndmask_b32_e32 v21, v21, v24, vcc
	v_cmp_class_f32_e32 vcc, v9, v149
	s_nop 1
	v_cndmask_b32_e32 v21, v21, v9, vcc
	v_pk_mul_f32 v[14:15], v[20:21], v[14:15]
	v_add_co_u32_e32 v20, vcc, s35, v12
	v_pk_fma_f32 v[14:15], v[16:17], v[0:1], v[14:15]
	s_nop 0
	v_addc_co_u32_e32 v21, vcc, 0, v13, vcc
	v_add_co_u32_e32 v0, vcc, s37, v12
	s_waitcnt vmcnt(23)
	v_mov_b32_e32 v16, v64
	v_mov_b32_e32 v17, v65
	s_nop 0
	v_addc_co_u32_e32 v1, vcc, 0, v13, vcc
	s_waitcnt vmcnt(22)
	v_mov_b32_e32 v24, v66
	v_mov_b32_e32 v25, v67
	s_nop 0
	v_lshlrev_b32_e32 v28, 16, v16
	v_and_b32_e32 v9, 0xffff0000, v16
	v_mul_f32_e32 v9, 0x3fb8aa3b, v9
	s_nop 0
	v_and_b32_e32 v27, 0xffff0000, v24
	v_lshlrev_b32_e32 v26, 16, v24
	v_mul_f32_e32 v24, 0x3fb8aa3b, v28
	v_exp_f32_e32 v28, v24
	v_and_b32_e32 v32, 0xffff0000, v17
	v_lshlrev_b32_e32 v17, 16, v17
	v_lshlrev_b32_e32 v16, 16, v25
	v_fma_f32 v24, -v28, v28, 1.0
	v_max_f32_e32 v24, 0, v24
	v_cmp_gt_f32_e32 vcc, s97, v24
	v_mul_f32_e32 v29, 0x4f800000, v24
	s_nop 0
	v_cndmask_b32_e32 v24, v24, v29, vcc
	v_sqrt_f32_e32 v29, v24
	s_nop 0
	v_add_u32_e32 v30, -1, v29
	v_fma_f32 v31, -v30, v29, v24
	v_cmp_ge_f32_e64 s[0:1], 0, v31
	v_add_u32_e32 v31, 1, v29
	s_nop 0
	v_cndmask_b32_e64 v30, v29, v30, s[0:1]
	v_fma_f32 v29, -v31, v29, v24
	v_cmp_lt_f32_e64 s[0:1], 0, v29
	s_nop 1
	v_cndmask_b32_e64 v29, v30, v31, s[0:1]
	v_mul_f32_e32 v30, 0x37800000, v29
	v_cndmask_b32_e32 v29, v29, v30, vcc
	v_cmp_class_f32_e32 vcc, v24, v149
	s_nop 1
	v_cndmask_b32_e32 v30, v29, v24, vcc
	v_exp_f32_e32 v29, v9
	s_nop 0
	v_fma_f32 v9, -v29, v29, 1.0
	v_max_f32_e32 v9, 0, v9
	v_cmp_gt_f32_e32 vcc, s97, v9
	v_mul_f32_e32 v24, 0x4f800000, v9
	v_pk_mul_f32 v[4:5], v[4:5], v[28:29]
	v_cndmask_b32_e32 v9, v9, v24, vcc
	v_sqrt_f32_e32 v24, v9
	s_nop 0
	v_add_u32_e32 v31, -1, v24
	v_fma_f32 v33, -v31, v24, v9
	v_cmp_ge_f32_e64 s[0:1], 0, v33
	v_add_u32_e32 v33, 1, v24
	s_nop 0
	v_cndmask_b32_e64 v31, v24, v31, s[0:1]
	v_fma_f32 v24, -v33, v24, v9
	v_cmp_lt_f32_e64 s[0:1], 0, v24
	s_nop 1
	v_cndmask_b32_e64 v24, v31, v33, s[0:1]
	v_mul_f32_e32 v31, 0x37800000, v24
	v_cndmask_b32_e32 v24, v24, v31, vcc
	v_cmp_class_f32_e32 vcc, v9, v149
	s_nop 1
	v_cndmask_b32_e32 v31, v24, v9, vcc
	v_pk_mul_f32 v[26:27], v[30:31], v[26:27]
	v_mul_f32_e32 v9, 0x3fb8aa3b, v17
	v_pk_fma_f32 v[18:19], v[18:19], v[28:29], v[26:27]
	v_exp_f32_e32 v26, v9
	s_nop 0
	v_fma_f32 v9, -v26, v26, 1.0
	v_max_f32_e32 v9, 0, v9
	v_cmp_gt_f32_e32 vcc, s97, v9
	v_mul_f32_e32 v17, 0x4f800000, v9
	s_nop 0
	v_cndmask_b32_e32 v9, v9, v17, vcc
	v_sqrt_f32_e32 v17, v9
	s_nop 0
	v_add_u32_e32 v24, -1, v17
	v_fma_f32 v27, -v24, v17, v9
	v_cmp_ge_f32_e64 s[0:1], 0, v27
	v_add_u32_e32 v27, 1, v17
	s_nop 0
	v_cndmask_b32_e64 v24, v17, v24, s[0:1]
	v_fma_f32 v17, -v27, v17, v9
	v_cmp_lt_f32_e64 s[0:1], 0, v17
	s_nop 1
	v_cndmask_b32_e64 v17, v24, v27, s[0:1]
	v_mul_f32_e32 v24, 0x37800000, v17
	v_cndmask_b32_e32 v17, v17, v24, vcc
	v_cmp_class_f32_e32 vcc, v9, v149
	s_nop 1
	v_cndmask_b32_e32 v24, v17, v9, vcc
	v_mul_f32_e32 v9, 0x3fb8aa3b, v32
	v_exp_f32_e32 v27, v9
	v_and_b32_e32 v17, 0xffff0000, v25
	v_fma_f32 v9, -v27, v27, 1.0
	v_max_f32_e32 v9, 0, v9
	v_cmp_gt_f32_e32 vcc, s97, v9
	v_mul_f32_e32 v25, 0x4f800000, v9
	v_pk_mul_f32 v[6:7], v[6:7], v[26:27]
	v_cndmask_b32_e32 v9, v9, v25, vcc
	v_sqrt_f32_e32 v25, v9
	s_nop 0
	v_add_u32_e32 v28, -1, v25
	v_fma_f32 v29, -v28, v25, v9
	v_cmp_ge_f32_e64 s[0:1], 0, v29
	v_add_u32_e32 v29, 1, v25
	s_nop 0
	v_cndmask_b32_e64 v28, v25, v28, s[0:1]
	v_fma_f32 v25, -v29, v25, v9
	v_cmp_lt_f32_e64 s[0:1], 0, v25
	s_nop 1
	v_cndmask_b32_e64 v25, v28, v29, s[0:1]
	v_mul_f32_e32 v28, 0x37800000, v25
	v_cndmask_b32_e32 v25, v25, v28, vcc
	v_cmp_class_f32_e32 vcc, v9, v149
	s_nop 1
	v_cndmask_b32_e32 v25, v25, v9, vcc
	v_pk_mul_f32 v[16:17], v[24:25], v[16:17]
	s_nop 0
	v_pk_fma_f32 v[14:15], v[14:15], v[26:27], v[16:17]
	s_waitcnt vmcnt(21)
	v_mov_b32_e32 v2, v68
	v_mov_b32_e32 v3, v69
	s_nop 0
	s_waitcnt vmcnt(20)
	v_mov_b32_e32 v16, v70
	v_mov_b32_e32 v17, v71
	s_nop 0
	v_and_b32_e32 v9, 0xffff0000, v2
	v_lshlrev_b32_e32 v2, 16, v2
	v_mul_f32_e32 v2, 0x3fb8aa3b, v2
	v_exp_f32_e32 v24, v2
	v_and_b32_e32 v28, 0xffff0000, v3
	v_lshlrev_b32_e32 v29, 16, v3
	s_nop 0
	v_and_b32_e32 v21, 0xffff0000, v16
	v_fma_f32 v2, -v24, v24, 1.0
	v_max_f32_e32 v2, 0, v2
	v_cmp_gt_f32_e32 vcc, s97, v2
	v_mul_f32_e32 v3, 0x4f800000, v2
	v_lshlrev_b32_e32 v20, 16, v16
	v_cndmask_b32_e32 v2, v2, v3, vcc
	v_sqrt_f32_e32 v3, v2
	v_lshlrev_b32_e32 v16, 16, v17
	v_and_b32_e32 v17, 0xffff0000, v17
	v_add_u32_e32 v25, -1, v3
	v_fma_f32 v26, -v25, v3, v2
	v_cmp_ge_f32_e64 s[0:1], 0, v26
	v_add_u32_e32 v26, 1, v3
	s_nop 0
	v_cndmask_b32_e64 v25, v3, v25, s[0:1]
	v_fma_f32 v3, -v26, v3, v2
	v_cmp_lt_f32_e64 s[0:1], 0, v3
	s_nop 1
	v_cndmask_b32_e64 v3, v25, v26, s[0:1]
	v_mul_f32_e32 v25, 0x37800000, v3
	v_cndmask_b32_e32 v3, v3, v25, vcc
	v_cmp_class_f32_e32 vcc, v2, v149
	s_nop 1
	v_cndmask_b32_e32 v26, v3, v2, vcc
	v_mul_f32_e32 v2, 0x3fb8aa3b, v9
	v_exp_f32_e32 v25, v2
	s_nop 0
	v_fma_f32 v2, -v25, v25, 1.0
	v_max_f32_e32 v2, 0, v2
	v_cmp_gt_f32_e32 vcc, s97, v2
	v_mul_f32_e32 v3, 0x4f800000, v2
	s_nop 0
	v_cndmask_b32_e32 v2, v2, v3, vcc
	v_sqrt_f32_e32 v3, v2
	s_nop 0
	v_add_u32_e32 v9, -1, v3
	v_fma_f32 v27, -v9, v3, v2
	v_cmp_ge_f32_e64 s[0:1], 0, v27
	v_add_u32_e32 v27, 1, v3
	s_nop 0
	v_cndmask_b32_e64 v9, v3, v9, s[0:1]
	v_fma_f32 v3, -v27, v3, v2
	v_cmp_lt_f32_e64 s[0:1], 0, v3
	s_nop 1
	v_cndmask_b32_e64 v3, v9, v27, s[0:1]
	v_mul_f32_e32 v9, 0x37800000, v3
	v_cndmask_b32_e32 v3, v3, v9, vcc
	v_cmp_class_f32_e32 vcc, v2, v149
	v_mul_f32_e32 v9, 0x3fb8aa3b, v29
	s_nop 0
	v_cndmask_b32_e32 v27, v3, v2, vcc
	v_pk_mul_f32 v[2:3], v[4:5], v[24:25]
	v_pk_mul_f32 v[4:5], v[26:27], v[20:21]
	s_nop 0
	v_pk_fma_f32 v[4:5], v[18:19], v[24:25], v[4:5]
	v_exp_f32_e32 v18, v9
	s_nop 0
	v_fma_f32 v9, -v18, v18, 1.0
	v_max_f32_e32 v9, 0, v9
	v_cmp_gt_f32_e32 vcc, s97, v9
	v_mul_f32_e32 v19, 0x4f800000, v9
	s_nop 0
	v_cndmask_b32_e32 v9, v9, v19, vcc
	v_sqrt_f32_e32 v19, v9
	s_nop 0
	v_add_u32_e32 v20, -1, v19
	v_fma_f32 v21, -v20, v19, v9
	v_cmp_ge_f32_e64 s[0:1], 0, v21
	v_add_u32_e32 v21, 1, v19
	s_nop 0
	v_cndmask_b32_e64 v20, v19, v20, s[0:1]
	v_fma_f32 v19, -v21, v19, v9
	v_cmp_lt_f32_e64 s[0:1], 0, v19
	s_nop 1
	v_cndmask_b32_e64 v19, v20, v21, s[0:1]
	v_mul_f32_e32 v20, 0x37800000, v19
	v_cndmask_b32_e32 v19, v19, v20, vcc
	v_cmp_class_f32_e32 vcc, v9, v149
	s_nop 1
	v_cndmask_b32_e32 v20, v19, v9, vcc
	v_mul_f32_e32 v9, 0x3fb8aa3b, v28
	v_exp_f32_e32 v19, v9
	s_nop 0
	v_fma_f32 v9, -v19, v19, 1.0
	v_max_f32_e32 v9, 0, v9
	v_cmp_gt_f32_e32 vcc, s97, v9
	v_mul_f32_e32 v21, 0x4f800000, v9
	v_pk_mul_f32 v[6:7], v[6:7], v[18:19]
	v_cndmask_b32_e32 v9, v9, v21, vcc
	v_sqrt_f32_e32 v21, v9
	s_nop 0
	v_add_u32_e32 v24, -1, v21
	v_fma_f32 v25, -v24, v21, v9
	v_cmp_ge_f32_e64 s[0:1], 0, v25
	v_add_u32_e32 v25, 1, v21
	s_nop 0
	v_cndmask_b32_e64 v24, v21, v24, s[0:1]
	v_fma_f32 v21, -v25, v21, v9
	v_cmp_lt_f32_e64 s[0:1], 0, v21
	s_nop 1
	v_cndmask_b32_e64 v21, v24, v25, s[0:1]
	v_mul_f32_e32 v24, 0x37800000, v21
	v_cndmask_b32_e32 v21, v21, v24, vcc
	v_cmp_class_f32_e32 vcc, v9, v149
	s_mov_b32 s0, 0x22cb9000
	s_nop 0
	v_cndmask_b32_e32 v21, v21, v9, vcc
	v_pk_mul_f32 v[16:17], v[20:21], v[16:17]
	s_nop 0
	v_pk_fma_f32 v[14:15], v[14:15], v[18:19], v[16:17]
	v_add_co_u32_e32 v16, vcc, s36, v12
	s_nop 1
	v_addc_co_u32_e32 v17, vcc, 0, v13, vcc
	v_add_co_u32_e32 v18, vcc, s0, v12
	s_nop 1
	v_addc_co_u32_e32 v19, vcc, 0, v13, vcc
	s_waitcnt vmcnt(19)
	v_mov_b32_e32 v20, v72
	v_mov_b32_e32 v21, v73
	s_waitcnt vmcnt(18)
	v_mov_b32_e32 v24, v74
	v_mov_b32_e32 v25, v75
	s_nop 0
	s_waitcnt vmcnt(17)
	v_mov_b32_e32 v16, v76
	v_mov_b32_e32 v17, v77
	s_nop 0
	s_waitcnt vmcnt(16)
	v_mov_b32_e32 v0, v78
	v_mov_b32_e32 v1, v79
	s_nop 0
	v_lshlrev_b32_e32 v28, 16, v20
	s_nop 0
	v_and_b32_e32 v27, 0xffff0000, v24
	v_lshlrev_b32_e32 v26, 16, v24
	v_mul_f32_e32 v24, 0x3fb8aa3b, v28
	v_exp_f32_e32 v28, v24
	v_and_b32_e32 v9, 0xffff0000, v20
	v_mul_f32_e32 v9, 0x3fb8aa3b, v9
	v_and_b32_e32 v32, 0xffff0000, v21
	v_fma_f32 v24, -v28, v28, 1.0
	v_max_f32_e32 v24, 0, v24
	v_cmp_gt_f32_e32 vcc, s97, v24
	v_mul_f32_e32 v29, 0x4f800000, v24
	v_lshlrev_b32_e32 v21, 16, v21
	v_cndmask_b32_e32 v24, v24, v29, vcc
	v_sqrt_f32_e32 v29, v24
	v_lshlrev_b32_e32 v20, 16, v25
	v_add_u32_e32 v30, -1, v29
	v_fma_f32 v31, -v30, v29, v24
	v_cmp_ge_f32_e64 s[0:1], 0, v31
	v_add_u32_e32 v31, 1, v29
	s_nop 0
	v_cndmask_b32_e64 v30, v29, v30, s[0:1]
	v_fma_f32 v29, -v31, v29, v24
	v_cmp_lt_f32_e64 s[0:1], 0, v29
	s_nop 1
	v_cndmask_b32_e64 v29, v30, v31, s[0:1]
	v_mul_f32_e32 v30, 0x37800000, v29
	v_cndmask_b32_e32 v29, v29, v30, vcc
	v_cmp_class_f32_e32 vcc, v24, v149
	s_nop 1
	v_cndmask_b32_e32 v30, v29, v24, vcc
	v_exp_f32_e32 v29, v9
	s_nop 0
	v_fma_f32 v9, -v29, v29, 1.0
	v_max_f32_e32 v9, 0, v9
	v_cmp_gt_f32_e32 vcc, s97, v9
	v_mul_f32_e32 v24, 0x4f800000, v9
	v_pk_mul_f32 v[2:3], v[2:3], v[28:29]
	v_cndmask_b32_e32 v9, v9, v24, vcc
	v_sqrt_f32_e32 v24, v9
	s_nop 0
	v_add_u32_e32 v31, -1, v24
	v_fma_f32 v33, -v31, v24, v9
	v_cmp_ge_f32_e64 s[0:1], 0, v33
	v_add_u32_e32 v33, 1, v24
	s_nop 0
	v_cndmask_b32_e64 v31, v24, v31, s[0:1]
	v_fma_f32 v24, -v33, v24, v9
	v_cmp_lt_f32_e64 s[0:1], 0, v24
	s_nop 1
	v_cndmask_b32_e64 v24, v31, v33, s[0:1]
	v_mul_f32_e32 v31, 0x37800000, v24
	v_cndmask_b32_e32 v24, v24, v31, vcc
	v_cmp_class_f32_e32 vcc, v9, v149
	s_nop 1
	v_cndmask_b32_e32 v31, v24, v9, vcc
	v_pk_mul_f32 v[26:27], v[30:31], v[26:27]
	v_mul_f32_e32 v9, 0x3fb8aa3b, v21
	v_pk_fma_f32 v[4:5], v[4:5], v[28:29], v[26:27]
	v_exp_f32_e32 v26, v9
	s_nop 0
	v_fma_f32 v9, -v26, v26, 1.0
	v_max_f32_e32 v9, 0, v9
	v_cmp_gt_f32_e32 vcc, s97, v9
	v_mul_f32_e32 v21, 0x4f800000, v9
	s_nop 0
	v_cndmask_b32_e32 v9, v9, v21, vcc
	v_sqrt_f32_e32 v21, v9
	s_nop 0
	v_add_u32_e32 v24, -1, v21
	v_fma_f32 v27, -v24, v21, v9
	v_cmp_ge_f32_e64 s[0:1], 0, v27
	v_add_u32_e32 v27, 1, v21
	s_nop 0
	v_cndmask_b32_e64 v24, v21, v24, s[0:1]
	v_fma_f32 v21, -v27, v21, v9
	v_cmp_lt_f32_e64 s[0:1], 0, v21
	s_nop 1
	v_cndmask_b32_e64 v21, v24, v27, s[0:1]
	v_mul_f32_e32 v24, 0x37800000, v21
	v_cndmask_b32_e32 v21, v21, v24, vcc
	v_cmp_class_f32_e32 vcc, v9, v149
	s_nop 1
	v_cndmask_b32_e32 v24, v21, v9, vcc
	v_mul_f32_e32 v9, 0x3fb8aa3b, v32
	v_exp_f32_e32 v27, v9
	v_and_b32_e32 v21, 0xffff0000, v25
	v_fma_f32 v9, -v27, v27, 1.0
	v_max_f32_e32 v9, 0, v9
	v_cmp_gt_f32_e32 vcc, s97, v9
	v_mul_f32_e32 v25, 0x4f800000, v9
	v_pk_mul_f32 v[6:7], v[6:7], v[26:27]
	v_cndmask_b32_e32 v9, v9, v25, vcc
	v_sqrt_f32_e32 v25, v9
	s_nop 0
	v_add_u32_e32 v28, -1, v25
	v_fma_f32 v29, -v28, v25, v9
	v_cmp_ge_f32_e64 s[0:1], 0, v29
	v_add_u32_e32 v29, 1, v25
	s_nop 0
	v_cndmask_b32_e64 v28, v25, v28, s[0:1]
	v_fma_f32 v25, -v29, v25, v9
	v_cmp_lt_f32_e64 s[0:1], 0, v25
	s_nop 1
	v_cndmask_b32_e64 v25, v28, v29, s[0:1]
	v_mul_f32_e32 v28, 0x37800000, v25
	v_cndmask_b32_e32 v25, v25, v28, vcc
	v_cmp_class_f32_e32 vcc, v9, v149
	s_nop 1
	v_cndmask_b32_e32 v25, v25, v9, vcc
	s_nop 0
	v_and_b32_e32 v9, 0xffff0000, v16
	v_lshlrev_b32_e32 v16, 16, v16
	v_mul_f32_e32 v16, 0x3fb8aa3b, v16
	v_exp_f32_e32 v16, v16
	v_pk_mul_f32 v[20:21], v[24:25], v[20:21]
	v_mul_f32_e32 v9, 0x3fb8aa3b, v9
	v_pk_fma_f32 v[14:15], v[14:15], v[26:27], v[20:21]
	v_and_b32_e32 v26, 0xffff0000, v17
	v_lshlrev_b32_e32 v27, 16, v17
	v_fma_f32 v17, -v16, v16, 1.0
	v_max_f32_e32 v17, 0, v17
	v_cmp_gt_f32_e32 vcc, s97, v17
	v_mul_f32_e32 v24, 0x4f800000, v17
	s_nop 0
	v_and_b32_e32 v21, 0xffff0000, v0
	v_cndmask_b32_e32 v17, v17, v24, vcc
	v_sqrt_f32_e32 v24, v17
	v_lshlrev_b32_e32 v20, 16, v0
	v_lshlrev_b32_e32 v0, 16, v1
	v_and_b32_e32 v1, 0xffff0000, v1
	v_add_u32_e32 v25, -1, v24
	v_fma_f32 v28, -v25, v24, v17
	v_cmp_ge_f32_e64 s[0:1], 0, v28
	v_add_u32_e32 v28, 1, v24
	s_nop 0
	v_cndmask_b32_e64 v25, v24, v25, s[0:1]
	v_fma_f32 v24, -v28, v24, v17
	v_cmp_lt_f32_e64 s[0:1], 0, v24
	s_nop 1
	v_cndmask_b32_e64 v24, v25, v28, s[0:1]
	v_mul_f32_e32 v25, 0x37800000, v24
	v_cndmask_b32_e32 v24, v24, v25, vcc
	v_cmp_class_f32_e32 vcc, v17, v149
	s_nop 1
	v_cndmask_b32_e32 v24, v24, v17, vcc
	v_exp_f32_e32 v17, v9
	s_nop 0
	v_fma_f32 v9, -v17, v17, 1.0
	v_max_f32_e32 v9, 0, v9
	v_cmp_gt_f32_e32 vcc, s97, v9
	v_mul_f32_e32 v25, 0x4f800000, v9
	v_pk_mul_f32 v[2:3], v[2:3], v[16:17]
	v_cndmask_b32_e32 v9, v9, v25, vcc
	v_sqrt_f32_e32 v25, v9
	s_nop 0
	v_add_u32_e32 v28, -1, v25
	v_fma_f32 v29, -v28, v25, v9
	v_cmp_ge_f32_e64 s[0:1], 0, v29
	v_add_u32_e32 v29, 1, v25
	s_nop 0
	v_cndmask_b32_e64 v28, v25, v28, s[0:1]
	v_fma_f32 v25, -v29, v25, v9
	v_cmp_lt_f32_e64 s[0:1], 0, v25
	s_nop 1
	v_cndmask_b32_e64 v25, v28, v29, s[0:1]
	v_mul_f32_e32 v28, 0x37800000, v25
	v_cndmask_b32_e32 v25, v25, v28, vcc
	v_cmp_class_f32_e32 vcc, v9, v149
	s_nop 1
	v_cndmask_b32_e32 v25, v25, v9, vcc
	v_pk_mul_f32 v[20:21], v[24:25], v[20:21]
	v_mul_f32_e32 v9, 0x3fb8aa3b, v27
	v_pk_fma_f32 v[4:5], v[4:5], v[16:17], v[20:21]
	v_exp_f32_e32 v16, v9
	s_nop 0
	v_fma_f32 v9, -v16, v16, 1.0
	v_max_f32_e32 v9, 0, v9
	v_cmp_gt_f32_e32 vcc, s97, v9
	v_mul_f32_e32 v17, 0x4f800000, v9
	s_nop 0
	v_cndmask_b32_e32 v9, v9, v17, vcc
	v_sqrt_f32_e32 v17, v9
	s_nop 0
	v_add_u32_e32 v20, -1, v17
	v_fma_f32 v21, -v20, v17, v9
	v_cmp_ge_f32_e64 s[0:1], 0, v21
	v_add_u32_e32 v21, 1, v17
	s_nop 0
	v_cndmask_b32_e64 v20, v17, v20, s[0:1]
	v_fma_f32 v17, -v21, v17, v9
	v_cmp_lt_f32_e64 s[0:1], 0, v17
	s_nop 1
	v_cndmask_b32_e64 v17, v20, v21, s[0:1]
	v_mul_f32_e32 v20, 0x37800000, v17
	v_cndmask_b32_e32 v17, v17, v20, vcc
	v_cmp_class_f32_e32 vcc, v9, v149
	s_nop 1
	v_cndmask_b32_e32 v20, v17, v9, vcc
	v_mul_f32_e32 v9, 0x3fb8aa3b, v26
	v_exp_f32_e32 v17, v9
	s_nop 0
	v_fma_f32 v9, -v17, v17, 1.0
	v_max_f32_e32 v9, 0, v9
	v_cmp_gt_f32_e32 vcc, s97, v9
	v_mul_f32_e32 v21, 0x4f800000, v9
	v_pk_mul_f32 v[6:7], v[6:7], v[16:17]
	v_cndmask_b32_e32 v9, v9, v21, vcc
	v_sqrt_f32_e32 v21, v9
	s_nop 0
	v_add_u32_e32 v24, -1, v21
	v_fma_f32 v25, -v24, v21, v9
	v_cmp_ge_f32_e64 s[0:1], 0, v25
	v_add_u32_e32 v25, 1, v21
	s_nop 0
	v_cndmask_b32_e64 v24, v21, v24, s[0:1]
	v_fma_f32 v21, -v25, v21, v9
	v_cmp_lt_f32_e64 s[0:1], 0, v21
	s_nop 1
	v_cndmask_b32_e64 v21, v24, v25, s[0:1]
	v_mul_f32_e32 v24, 0x37800000, v21
	v_cndmask_b32_e32 v21, v21, v24, vcc
	v_cmp_class_f32_e32 vcc, v9, v149
	s_mov_b32 s0, 0x24d39000
	s_nop 0
	v_cndmask_b32_e32 v21, v21, v9, vcc
	v_pk_mul_f32 v[0:1], v[20:21], v[0:1]
	v_add_co_u32_e32 v20, vcc, s0, v12
	s_mov_b32 s0, 0x24d3a000
	s_nop 0
	v_addc_co_u32_e32 v21, vcc, 0, v13, vcc
	v_pk_fma_f32 v[14:15], v[14:15], v[16:17], v[0:1]
	v_add_co_u32_e32 v0, vcc, s0, v12
	s_waitcnt vmcnt(15)
	v_mov_b32_e32 v16, v80
	v_mov_b32_e32 v17, v81
	s_nop 0
	v_addc_co_u32_e32 v1, vcc, 0, v13, vcc
	s_waitcnt vmcnt(14)
	v_mov_b32_e32 v24, v82
	v_mov_b32_e32 v25, v83
	s_nop 0
	v_lshlrev_b32_e32 v28, 16, v16
	v_and_b32_e32 v9, 0xffff0000, v16
	v_mul_f32_e32 v9, 0x3fb8aa3b, v9
	s_nop 0
	v_and_b32_e32 v27, 0xffff0000, v24
	v_lshlrev_b32_e32 v26, 16, v24
	v_mul_f32_e32 v24, 0x3fb8aa3b, v28
	v_exp_f32_e32 v28, v24
	v_and_b32_e32 v32, 0xffff0000, v17
	v_lshlrev_b32_e32 v17, 16, v17
	v_lshlrev_b32_e32 v16, 16, v25
	v_fma_f32 v24, -v28, v28, 1.0
	v_max_f32_e32 v24, 0, v24
	v_cmp_gt_f32_e32 vcc, s97, v24
	v_mul_f32_e32 v29, 0x4f800000, v24
	s_nop 0
	v_cndmask_b32_e32 v24, v24, v29, vcc
	v_sqrt_f32_e32 v29, v24
	s_nop 0
	v_add_u32_e32 v30, -1, v29
	v_fma_f32 v31, -v30, v29, v24
	v_cmp_ge_f32_e64 s[0:1], 0, v31
	v_add_u32_e32 v31, 1, v29
	s_nop 0
	v_cndmask_b32_e64 v30, v29, v30, s[0:1]
	v_fma_f32 v29, -v31, v29, v24
	v_cmp_lt_f32_e64 s[0:1], 0, v29
	s_nop 1
	v_cndmask_b32_e64 v29, v30, v31, s[0:1]
	v_mul_f32_e32 v30, 0x37800000, v29
	v_cndmask_b32_e32 v29, v29, v30, vcc
	v_cmp_class_f32_e32 vcc, v24, v149
	s_nop 1
	v_cndmask_b32_e32 v30, v29, v24, vcc
	v_exp_f32_e32 v29, v9
	s_nop 0
	v_fma_f32 v9, -v29, v29, 1.0
	v_max_f32_e32 v9, 0, v9
	v_cmp_gt_f32_e32 vcc, s97, v9
	v_mul_f32_e32 v24, 0x4f800000, v9
	v_pk_mul_f32 v[2:3], v[2:3], v[28:29]
	v_cndmask_b32_e32 v9, v9, v24, vcc
	v_sqrt_f32_e32 v24, v9
	s_nop 0
	v_add_u32_e32 v31, -1, v24
	v_fma_f32 v33, -v31, v24, v9
	v_cmp_ge_f32_e64 s[0:1], 0, v33
	v_add_u32_e32 v33, 1, v24
	s_nop 0
	v_cndmask_b32_e64 v31, v24, v31, s[0:1]
	v_fma_f32 v24, -v33, v24, v9
	v_cmp_lt_f32_e64 s[0:1], 0, v24
	s_nop 1
	v_cndmask_b32_e64 v24, v31, v33, s[0:1]
	v_mul_f32_e32 v31, 0x37800000, v24
	v_cndmask_b32_e32 v24, v24, v31, vcc
	v_cmp_class_f32_e32 vcc, v9, v149
	s_nop 1
	v_cndmask_b32_e32 v31, v24, v9, vcc
	v_pk_mul_f32 v[26:27], v[30:31], v[26:27]
	s_nop 0
	v_pk_fma_f32 v[26:27], v[4:5], v[28:29], v[26:27]
	v_mul_f32_e32 v4, 0x3fb8aa3b, v17
	v_exp_f32_e32 v4, v4
	s_nop 0
	v_fma_f32 v5, -v4, v4, 1.0
	v_max_f32_e32 v5, 0, v5
	v_cmp_gt_f32_e32 vcc, s97, v5
	v_mul_f32_e32 v9, 0x4f800000, v5
	s_nop 0
	v_cndmask_b32_e32 v5, v5, v9, vcc
	v_sqrt_f32_e32 v9, v5
	s_nop 0
	v_add_u32_e32 v17, -1, v9
	v_fma_f32 v24, -v17, v9, v5
	v_cmp_ge_f32_e64 s[0:1], 0, v24
	v_add_u32_e32 v24, 1, v9
	s_nop 0
	v_cndmask_b32_e64 v17, v9, v17, s[0:1]
	v_fma_f32 v9, -v24, v9, v5
	v_cmp_lt_f32_e64 s[0:1], 0, v9
	s_nop 1
	v_cndmask_b32_e64 v9, v17, v24, s[0:1]
	v_mul_f32_e32 v17, 0x37800000, v9
	v_cndmask_b32_e32 v9, v9, v17, vcc
	v_cmp_class_f32_e32 vcc, v5, v149
	v_and_b32_e32 v17, 0xffff0000, v25
	s_nop 0
	v_cndmask_b32_e32 v24, v9, v5, vcc
	v_mul_f32_e32 v5, 0x3fb8aa3b, v32
	v_exp_f32_e32 v5, v5
	s_nop 0
	v_pk_mul_f32 v[28:29], v[6:7], v[4:5]
	v_fma_f32 v6, -v5, v5, 1.0
	v_max_f32_e32 v6, 0, v6
	v_cmp_gt_f32_e32 vcc, s97, v6
	v_mul_f32_e32 v7, 0x4f800000, v6
	s_nop 0
	v_cndmask_b32_e32 v6, v6, v7, vcc
	v_sqrt_f32_e32 v7, v6
	s_nop 0
	v_add_u32_e32 v9, -1, v7
	v_fma_f32 v25, -v9, v7, v6
	v_cmp_ge_f32_e64 s[0:1], 0, v25
	v_add_u32_e32 v25, 1, v7
	s_nop 0
	v_cndmask_b32_e64 v9, v7, v9, s[0:1]
	v_fma_f32 v7, -v25, v7, v6
	v_cmp_lt_f32_e64 s[0:1], 0, v7
	s_nop 1
	v_cndmask_b32_e64 v7, v9, v25, s[0:1]
	v_mul_f32_e32 v9, 0x37800000, v7
	v_cndmask_b32_e32 v7, v7, v9, vcc
	v_cmp_class_f32_e32 vcc, v6, v149
	s_nop 1
	v_cndmask_b32_e32 v25, v7, v6, vcc
	v_pk_mul_f32 v[6:7], v[24:25], v[16:17]
	s_nop 0
	v_pk_fma_f32 v[16:17], v[14:15], v[4:5], v[6:7]
	s_waitcnt vmcnt(13)
	v_mov_b32_e32 v4, v84
	v_mov_b32_e32 v5, v85
	s_nop 0
	s_waitcnt vmcnt(12)
	v_mov_b32_e32 v18, v86
	v_mov_b32_e32 v19, v87
	s_nop 0
	v_and_b32_e32 v9, 0xffff0000, v4
	v_lshlrev_b32_e32 v4, 16, v4
	v_mul_f32_e32 v4, 0x3fb8aa3b, v4
	v_exp_f32_e32 v14, v4
	v_and_b32_e32 v24, 0xffff0000, v5
	v_lshlrev_b32_e32 v25, 16, v5
	s_nop 0
	v_and_b32_e32 v7, 0xffff0000, v18
	v_fma_f32 v4, -v14, v14, 1.0
	v_max_f32_e32 v4, 0, v4
	v_cmp_gt_f32_e32 vcc, s97, v4
	v_mul_f32_e32 v5, 0x4f800000, v4
	v_lshlrev_b32_e32 v6, 16, v18
	v_cndmask_b32_e32 v4, v4, v5, vcc
	v_sqrt_f32_e32 v5, v4
	v_lshlrev_b32_e32 v18, 16, v19
	v_and_b32_e32 v19, 0xffff0000, v19
	v_add_u32_e32 v15, -1, v5
	v_fma_f32 v20, -v15, v5, v4
	v_cmp_ge_f32_e64 s[0:1], 0, v20
	v_add_u32_e32 v20, 1, v5
	s_nop 0
	v_cndmask_b32_e64 v15, v5, v15, s[0:1]
	v_fma_f32 v5, -v20, v5, v4
	v_cmp_lt_f32_e64 s[0:1], 0, v5
	s_nop 1
	v_cndmask_b32_e64 v5, v15, v20, s[0:1]
	v_mul_f32_e32 v15, 0x37800000, v5
	v_cndmask_b32_e32 v5, v5, v15, vcc
	v_cmp_class_f32_e32 vcc, v4, v149
	s_nop 1
	v_cndmask_b32_e32 v20, v5, v4, vcc
	v_mul_f32_e32 v4, 0x3fb8aa3b, v9
	v_exp_f32_e32 v15, v4
	s_nop 0
	v_fma_f32 v4, -v15, v15, 1.0
	v_max_f32_e32 v4, 0, v4
	v_cmp_gt_f32_e32 vcc, s97, v4
	v_mul_f32_e32 v5, 0x4f800000, v4
	s_nop 0
	v_cndmask_b32_e32 v4, v4, v5, vcc
	v_sqrt_f32_e32 v5, v4
	s_nop 0
	v_add_u32_e32 v9, -1, v5
	v_fma_f32 v21, -v9, v5, v4
	v_cmp_ge_f32_e64 s[0:1], 0, v21
	v_add_u32_e32 v21, 1, v5
	s_nop 0
	v_cndmask_b32_e64 v9, v5, v9, s[0:1]
	v_fma_f32 v5, -v21, v5, v4
	v_cmp_lt_f32_e64 s[0:1], 0, v5
	s_nop 1
	v_cndmask_b32_e64 v5, v9, v21, s[0:1]
	v_mul_f32_e32 v9, 0x37800000, v5
	v_cndmask_b32_e32 v5, v5, v9, vcc
	v_cmp_class_f32_e32 vcc, v4, v149
	s_nop 1
	v_cndmask_b32_e32 v21, v5, v4, vcc
	v_pk_mul_f32 v[4:5], v[2:3], v[14:15]
	v_pk_mul_f32 v[2:3], v[20:21], v[6:7]
	s_nop 0
	v_pk_fma_f32 v[6:7], v[26:27], v[14:15], v[2:3]
	v_mul_f32_e32 v2, 0x3fb8aa3b, v25
	v_exp_f32_e32 v2, v2
	s_nop 0
	v_fma_f32 v3, -v2, v2, 1.0
	v_max_f32_e32 v3, 0, v3
	v_cmp_gt_f32_e32 vcc, s97, v3
	v_mul_f32_e32 v9, 0x4f800000, v3
	s_nop 0
	v_cndmask_b32_e32 v3, v3, v9, vcc
	v_sqrt_f32_e32 v9, v3
	s_nop 0
	v_add_u32_e32 v14, -1, v9
	v_fma_f32 v15, -v14, v9, v3
	v_cmp_ge_f32_e64 s[0:1], 0, v15
	v_add_u32_e32 v15, 1, v9
	s_nop 0
	v_cndmask_b32_e64 v14, v9, v14, s[0:1]
	v_fma_f32 v9, -v15, v9, v3
	v_cmp_lt_f32_e64 s[0:1], 0, v9
	s_nop 1
	v_cndmask_b32_e64 v9, v14, v15, s[0:1]
	v_mul_f32_e32 v14, 0x37800000, v9
	v_cndmask_b32_e32 v9, v9, v14, vcc
	v_cmp_class_f32_e32 vcc, v3, v149
	s_nop 1
	v_cndmask_b32_e32 v20, v9, v3, vcc
	v_mul_f32_e32 v3, 0x3fb8aa3b, v24
	v_exp_f32_e32 v3, v3
	s_nop 0
	v_fma_f32 v9, -v3, v3, 1.0
	v_max_f32_e32 v9, 0, v9
	v_cmp_gt_f32_e32 vcc, s97, v9
	v_mul_f32_e32 v21, 0x4f800000, v9
	v_pk_mul_f32 v[14:15], v[28:29], v[2:3]
	v_cndmask_b32_e32 v9, v9, v21, vcc
	v_sqrt_f32_e32 v21, v9
	s_nop 0
	v_add_u32_e32 v24, -1, v21
	v_fma_f32 v25, -v24, v21, v9
	v_cmp_ge_f32_e64 s[0:1], 0, v25
	v_add_u32_e32 v25, 1, v21
	s_nop 0
	v_cndmask_b32_e64 v24, v21, v24, s[0:1]
	v_fma_f32 v21, -v25, v21, v9
	v_cmp_lt_f32_e64 s[0:1], 0, v21
	s_nop 1
	v_cndmask_b32_e64 v21, v24, v25, s[0:1]
	v_mul_f32_e32 v24, 0x37800000, v21
	v_cndmask_b32_e32 v21, v21, v24, vcc
	v_cmp_class_f32_e32 vcc, v9, v149
	s_mov_b32 s0, 0x22cba000
	s_nop 0
	v_cndmask_b32_e32 v21, v21, v9, vcc
	v_pk_mul_f32 v[18:19], v[20:21], v[18:19]
	s_nop 0
	v_pk_fma_f32 v[16:17], v[16:17], v[2:3], v[18:19]
	v_add_co_u32_e32 v18, vcc, s0, v12
	s_mov_b32 s0, 0x22cbb000
	s_nop 0
	v_addc_co_u32_e32 v19, vcc, 0, v13, vcc
	v_add_co_u32_e32 v2, vcc, s0, v12
	s_nop 1
	v_addc_co_u32_e32 v3, vcc, 0, v13, vcc
	s_waitcnt vmcnt(11)
	v_mov_b32_e32 v20, v88
	v_mov_b32_e32 v21, v89
	s_waitcnt vmcnt(10)
	v_mov_b32_e32 v24, v90
	v_mov_b32_e32 v25, v91
	s_nop 0
	s_waitcnt vmcnt(9)
	v_mov_b32_e32 v18, v92
	v_mov_b32_e32 v19, v93
	s_nop 0
	s_waitcnt vmcnt(8)
	v_mov_b32_e32 v0, v94
	v_mov_b32_e32 v1, v95
	s_nop 0
	v_lshlrev_b32_e32 v28, 16, v20
	s_nop 0
	v_and_b32_e32 v27, 0xffff0000, v24
	v_lshlrev_b32_e32 v26, 16, v24
	v_mul_f32_e32 v24, 0x3fb8aa3b, v28
	v_exp_f32_e32 v28, v24
	v_and_b32_e32 v9, 0xffff0000, v20
	v_mul_f32_e32 v9, 0x3fb8aa3b, v9
	v_and_b32_e32 v32, 0xffff0000, v21
	v_fma_f32 v24, -v28, v28, 1.0
	v_max_f32_e32 v24, 0, v24
	v_cmp_gt_f32_e32 vcc, s97, v24
	v_mul_f32_e32 v29, 0x4f800000, v24
	v_lshlrev_b32_e32 v21, 16, v21
	v_cndmask_b32_e32 v24, v24, v29, vcc
	v_sqrt_f32_e32 v29, v24
	v_lshlrev_b32_e32 v20, 16, v25
	v_add_u32_e32 v30, -1, v29
	v_fma_f32 v31, -v30, v29, v24
	v_cmp_ge_f32_e64 s[0:1], 0, v31
	v_add_u32_e32 v31, 1, v29
	s_nop 0
	v_cndmask_b32_e64 v30, v29, v30, s[0:1]
	v_fma_f32 v29, -v31, v29, v24
	v_cmp_lt_f32_e64 s[0:1], 0, v29
	s_nop 1
	v_cndmask_b32_e64 v29, v30, v31, s[0:1]
	v_mul_f32_e32 v30, 0x37800000, v29
	v_cndmask_b32_e32 v29, v29, v30, vcc
	v_cmp_class_f32_e32 vcc, v24, v149
	s_nop 1
	v_cndmask_b32_e32 v30, v29, v24, vcc
	v_exp_f32_e32 v29, v9
	s_nop 0
	v_fma_f32 v9, -v29, v29, 1.0
	v_max_f32_e32 v9, 0, v9
	v_cmp_gt_f32_e32 vcc, s97, v9
	v_mul_f32_e32 v24, 0x4f800000, v9
	v_pk_mul_f32 v[4:5], v[4:5], v[28:29]
	v_cndmask_b32_e32 v9, v9, v24, vcc
	v_sqrt_f32_e32 v24, v9
	s_nop 0
	v_add_u32_e32 v31, -1, v24
	v_fma_f32 v33, -v31, v24, v9
	v_cmp_ge_f32_e64 s[0:1], 0, v33
	v_add_u32_e32 v33, 1, v24
	s_nop 0
	v_cndmask_b32_e64 v31, v24, v31, s[0:1]
	v_fma_f32 v24, -v33, v24, v9
	v_cmp_lt_f32_e64 s[0:1], 0, v24
	s_nop 1
	v_cndmask_b32_e64 v24, v31, v33, s[0:1]
	v_mul_f32_e32 v31, 0x37800000, v24
	v_cndmask_b32_e32 v24, v24, v31, vcc
	v_cmp_class_f32_e32 vcc, v9, v149
	s_nop 1
	v_cndmask_b32_e32 v31, v24, v9, vcc
	v_pk_mul_f32 v[26:27], v[30:31], v[26:27]
	v_mul_f32_e32 v9, 0x3fb8aa3b, v21
	v_pk_fma_f32 v[6:7], v[6:7], v[28:29], v[26:27]
	v_exp_f32_e32 v26, v9
	s_nop 0
	v_fma_f32 v9, -v26, v26, 1.0
	v_max_f32_e32 v9, 0, v9
	v_cmp_gt_f32_e32 vcc, s97, v9
	v_mul_f32_e32 v21, 0x4f800000, v9
	s_nop 0
	v_cndmask_b32_e32 v9, v9, v21, vcc
	v_sqrt_f32_e32 v21, v9
	s_nop 0
	v_add_u32_e32 v24, -1, v21
	v_fma_f32 v27, -v24, v21, v9
	v_cmp_ge_f32_e64 s[0:1], 0, v27
	v_add_u32_e32 v27, 1, v21
	s_nop 0
	v_cndmask_b32_e64 v24, v21, v24, s[0:1]
	v_fma_f32 v21, -v27, v21, v9
	v_cmp_lt_f32_e64 s[0:1], 0, v21
	s_nop 1
	v_cndmask_b32_e64 v21, v24, v27, s[0:1]
	v_mul_f32_e32 v24, 0x37800000, v21
	v_cndmask_b32_e32 v21, v21, v24, vcc
	v_cmp_class_f32_e32 vcc, v9, v149
	s_nop 1
	v_cndmask_b32_e32 v24, v21, v9, vcc
	v_mul_f32_e32 v9, 0x3fb8aa3b, v32
	v_exp_f32_e32 v27, v9
	v_and_b32_e32 v21, 0xffff0000, v25
	v_fma_f32 v9, -v27, v27, 1.0
	v_max_f32_e32 v9, 0, v9
	v_cmp_gt_f32_e32 vcc, s97, v9
	v_mul_f32_e32 v25, 0x4f800000, v9
	v_pk_mul_f32 v[14:15], v[14:15], v[26:27]
	v_cndmask_b32_e32 v9, v9, v25, vcc
	v_sqrt_f32_e32 v25, v9
	s_nop 0
	v_add_u32_e32 v28, -1, v25
	v_fma_f32 v29, -v28, v25, v9
	v_cmp_ge_f32_e64 s[0:1], 0, v29
	v_add_u32_e32 v29, 1, v25
	s_nop 0
	v_cndmask_b32_e64 v28, v25, v28, s[0:1]
	v_fma_f32 v25, -v29, v25, v9
	v_cmp_lt_f32_e64 s[0:1], 0, v25
	s_nop 1
	v_cndmask_b32_e64 v25, v28, v29, s[0:1]
	v_mul_f32_e32 v28, 0x37800000, v25
	v_cndmask_b32_e32 v25, v25, v28, vcc
	v_cmp_class_f32_e32 vcc, v9, v149
	s_nop 1
	v_cndmask_b32_e32 v25, v25, v9, vcc
	s_nop 0
	v_and_b32_e32 v9, 0xffff0000, v18
	v_lshlrev_b32_e32 v18, 16, v18
	v_mul_f32_e32 v18, 0x3fb8aa3b, v18
	v_exp_f32_e32 v18, v18
	v_pk_mul_f32 v[20:21], v[24:25], v[20:21]
	v_mul_f32_e32 v9, 0x3fb8aa3b, v9
	v_pk_fma_f32 v[16:17], v[16:17], v[26:27], v[20:21]
	v_and_b32_e32 v26, 0xffff0000, v19
	v_lshlrev_b32_e32 v27, 16, v19
	v_fma_f32 v19, -v18, v18, 1.0
	v_max_f32_e32 v19, 0, v19
	v_cmp_gt_f32_e32 vcc, s97, v19
	v_mul_f32_e32 v24, 0x4f800000, v19
	s_nop 0
	v_and_b32_e32 v21, 0xffff0000, v0
	v_cndmask_b32_e32 v19, v19, v24, vcc
	v_sqrt_f32_e32 v24, v19
	v_lshlrev_b32_e32 v20, 16, v0
	v_lshlrev_b32_e32 v0, 16, v1
	v_and_b32_e32 v1, 0xffff0000, v1
	v_add_u32_e32 v25, -1, v24
	v_fma_f32 v28, -v25, v24, v19
	v_cmp_ge_f32_e64 s[0:1], 0, v28
	v_add_u32_e32 v28, 1, v24
	s_nop 0
	v_cndmask_b32_e64 v25, v24, v25, s[0:1]
	v_fma_f32 v24, -v28, v24, v19
	v_cmp_lt_f32_e64 s[0:1], 0, v24
	s_nop 1
	v_cndmask_b32_e64 v24, v25, v28, s[0:1]
	v_mul_f32_e32 v25, 0x37800000, v24
	v_cndmask_b32_e32 v24, v24, v25, vcc
	v_cmp_class_f32_e32 vcc, v19, v149
	s_nop 1
	v_cndmask_b32_e32 v24, v24, v19, vcc
	v_exp_f32_e32 v19, v9
	s_nop 0
	v_fma_f32 v9, -v19, v19, 1.0
	v_max_f32_e32 v9, 0, v9
	v_cmp_gt_f32_e32 vcc, s97, v9
	v_mul_f32_e32 v25, 0x4f800000, v9
	v_pk_mul_f32 v[4:5], v[4:5], v[18:19]
	v_cndmask_b32_e32 v9, v9, v25, vcc
	v_sqrt_f32_e32 v25, v9
	s_nop 0
	v_add_u32_e32 v28, -1, v25
	v_fma_f32 v29, -v28, v25, v9
	v_cmp_ge_f32_e64 s[0:1], 0, v29
	v_add_u32_e32 v29, 1, v25
	s_nop 0
	v_cndmask_b32_e64 v28, v25, v28, s[0:1]
	v_fma_f32 v25, -v29, v25, v9
	v_cmp_lt_f32_e64 s[0:1], 0, v25
	s_nop 1
	v_cndmask_b32_e64 v25, v28, v29, s[0:1]
	v_mul_f32_e32 v28, 0x37800000, v25
	v_cndmask_b32_e32 v25, v25, v28, vcc
	v_cmp_class_f32_e32 vcc, v9, v149
	s_nop 1
	v_cndmask_b32_e32 v25, v25, v9, vcc
	v_pk_mul_f32 v[20:21], v[24:25], v[20:21]
	v_mul_f32_e32 v9, 0x3fb8aa3b, v27
	v_pk_fma_f32 v[6:7], v[6:7], v[18:19], v[20:21]
	v_exp_f32_e32 v18, v9
	s_nop 0
	v_fma_f32 v9, -v18, v18, 1.0
	v_max_f32_e32 v9, 0, v9
	v_cmp_gt_f32_e32 vcc, s97, v9
	v_mul_f32_e32 v19, 0x4f800000, v9
	s_nop 0
	v_cndmask_b32_e32 v9, v9, v19, vcc
	v_sqrt_f32_e32 v19, v9
	s_nop 0
	v_add_u32_e32 v20, -1, v19
	v_fma_f32 v21, -v20, v19, v9
	v_cmp_ge_f32_e64 s[0:1], 0, v21
	v_add_u32_e32 v21, 1, v19
	s_nop 0
	v_cndmask_b32_e64 v20, v19, v20, s[0:1]
	v_fma_f32 v19, -v21, v19, v9
	v_cmp_lt_f32_e64 s[0:1], 0, v19
	s_nop 1
	v_cndmask_b32_e64 v19, v20, v21, s[0:1]
	v_mul_f32_e32 v20, 0x37800000, v19
	v_cndmask_b32_e32 v19, v19, v20, vcc
	v_cmp_class_f32_e32 vcc, v9, v149
	s_nop 1
	v_cndmask_b32_e32 v20, v19, v9, vcc
	v_mul_f32_e32 v9, 0x3fb8aa3b, v26
	v_exp_f32_e32 v19, v9
	s_nop 0
	v_fma_f32 v9, -v19, v19, 1.0
	v_max_f32_e32 v9, 0, v9
	v_cmp_gt_f32_e32 vcc, s97, v9
	v_mul_f32_e32 v21, 0x4f800000, v9
	v_pk_mul_f32 v[14:15], v[14:15], v[18:19]
	v_cndmask_b32_e32 v9, v9, v21, vcc
	v_sqrt_f32_e32 v21, v9
	s_nop 0
	v_add_u32_e32 v24, -1, v21
	v_fma_f32 v25, -v24, v21, v9
	v_cmp_ge_f32_e64 s[0:1], 0, v25
	v_add_u32_e32 v25, 1, v21
	s_nop 0
	v_cndmask_b32_e64 v24, v21, v24, s[0:1]
	v_fma_f32 v21, -v25, v21, v9
	v_cmp_lt_f32_e64 s[0:1], 0, v21
	s_nop 1
	v_cndmask_b32_e64 v21, v24, v25, s[0:1]
	v_mul_f32_e32 v24, 0x37800000, v21
	v_cndmask_b32_e32 v21, v21, v24, vcc
	v_cmp_class_f32_e32 vcc, v9, v149
	s_mov_b32 s0, 0x24d3b000
	s_nop 0
	v_cndmask_b32_e32 v21, v21, v9, vcc
	v_pk_mul_f32 v[0:1], v[20:21], v[0:1]
	v_add_co_u32_e32 v20, vcc, s0, v12
	s_mov_b32 s0, 0x24d3c000
	s_nop 0
	v_addc_co_u32_e32 v21, vcc, 0, v13, vcc
	v_pk_fma_f32 v[16:17], v[16:17], v[18:19], v[0:1]
	v_add_co_u32_e32 v0, vcc, s0, v12
	s_waitcnt vmcnt(7)
	v_mov_b32_e32 v18, v100
	v_mov_b32_e32 v19, v101
	s_nop 0
	v_addc_co_u32_e32 v1, vcc, 0, v13, vcc
	s_waitcnt vmcnt(6)
	v_mov_b32_e32 v24, v102
	v_mov_b32_e32 v25, v103
	s_nop 0
	v_lshlrev_b32_e32 v28, 16, v18
	v_and_b32_e32 v9, 0xffff0000, v18
	v_mul_f32_e32 v9, 0x3fb8aa3b, v9
	s_nop 0
	v_and_b32_e32 v27, 0xffff0000, v24
	v_lshlrev_b32_e32 v26, 16, v24
	v_mul_f32_e32 v24, 0x3fb8aa3b, v28
	v_exp_f32_e32 v28, v24
	v_and_b32_e32 v32, 0xffff0000, v19
	v_lshlrev_b32_e32 v19, 16, v19
	v_lshlrev_b32_e32 v18, 16, v25
	v_fma_f32 v24, -v28, v28, 1.0
	v_max_f32_e32 v24, 0, v24
	v_cmp_gt_f32_e32 vcc, s97, v24
	v_mul_f32_e32 v29, 0x4f800000, v24
	s_nop 0
	v_cndmask_b32_e32 v24, v24, v29, vcc
	v_sqrt_f32_e32 v29, v24
	s_nop 0
	v_add_u32_e32 v30, -1, v29
	v_fma_f32 v31, -v30, v29, v24
	v_cmp_ge_f32_e64 s[0:1], 0, v31
	v_add_u32_e32 v31, 1, v29
	s_nop 0
	v_cndmask_b32_e64 v30, v29, v30, s[0:1]
	v_fma_f32 v29, -v31, v29, v24
	v_cmp_lt_f32_e64 s[0:1], 0, v29
	s_nop 1
	v_cndmask_b32_e64 v29, v30, v31, s[0:1]
	v_mul_f32_e32 v30, 0x37800000, v29
	v_cndmask_b32_e32 v29, v29, v30, vcc
	v_cmp_class_f32_e32 vcc, v24, v149
	s_nop 1
	v_cndmask_b32_e32 v30, v29, v24, vcc
	v_exp_f32_e32 v29, v9
	s_nop 0
	v_fma_f32 v9, -v29, v29, 1.0
	v_max_f32_e32 v9, 0, v9
	v_cmp_gt_f32_e32 vcc, s97, v9
	v_mul_f32_e32 v24, 0x4f800000, v9
	v_pk_mul_f32 v[4:5], v[4:5], v[28:29]
	v_cndmask_b32_e32 v9, v9, v24, vcc
	v_sqrt_f32_e32 v24, v9
	s_nop 0
	v_add_u32_e32 v31, -1, v24
	v_fma_f32 v33, -v31, v24, v9
	v_cmp_ge_f32_e64 s[0:1], 0, v33
	v_add_u32_e32 v33, 1, v24
	s_nop 0
	v_cndmask_b32_e64 v31, v24, v31, s[0:1]
	v_fma_f32 v24, -v33, v24, v9
	v_cmp_lt_f32_e64 s[0:1], 0, v24
	s_nop 1
	v_cndmask_b32_e64 v24, v31, v33, s[0:1]
	v_mul_f32_e32 v31, 0x37800000, v24
	v_cndmask_b32_e32 v24, v24, v31, vcc
	v_cmp_class_f32_e32 vcc, v9, v149
	s_nop 1
	v_cndmask_b32_e32 v31, v24, v9, vcc
	v_pk_mul_f32 v[26:27], v[30:31], v[26:27]
	v_mul_f32_e32 v9, 0x3fb8aa3b, v19
	v_pk_fma_f32 v[6:7], v[6:7], v[28:29], v[26:27]
	v_exp_f32_e32 v26, v9
	s_nop 0
	v_fma_f32 v9, -v26, v26, 1.0
	v_max_f32_e32 v9, 0, v9
	v_cmp_gt_f32_e32 vcc, s97, v9
	v_mul_f32_e32 v19, 0x4f800000, v9
	s_nop 0
	v_cndmask_b32_e32 v9, v9, v19, vcc
	v_sqrt_f32_e32 v19, v9
	s_nop 0
	v_add_u32_e32 v24, -1, v19
	v_fma_f32 v27, -v24, v19, v9
	v_cmp_ge_f32_e64 s[0:1], 0, v27
	v_add_u32_e32 v27, 1, v19
	s_nop 0
	v_cndmask_b32_e64 v24, v19, v24, s[0:1]
	v_fma_f32 v19, -v27, v19, v9
	v_cmp_lt_f32_e64 s[0:1], 0, v19
	s_nop 1
	v_cndmask_b32_e64 v19, v24, v27, s[0:1]
	v_mul_f32_e32 v24, 0x37800000, v19
	v_cndmask_b32_e32 v19, v19, v24, vcc
	v_cmp_class_f32_e32 vcc, v9, v149
	s_nop 1
	v_cndmask_b32_e32 v24, v19, v9, vcc
	v_mul_f32_e32 v9, 0x3fb8aa3b, v32
	v_exp_f32_e32 v27, v9
	v_and_b32_e32 v19, 0xffff0000, v25
	v_fma_f32 v9, -v27, v27, 1.0
	v_max_f32_e32 v9, 0, v9
	v_cmp_gt_f32_e32 vcc, s97, v9
	v_mul_f32_e32 v25, 0x4f800000, v9
	v_pk_mul_f32 v[14:15], v[14:15], v[26:27]
	v_cndmask_b32_e32 v9, v9, v25, vcc
	v_sqrt_f32_e32 v25, v9
	s_nop 0
	v_add_u32_e32 v28, -1, v25
	v_fma_f32 v29, -v28, v25, v9
	v_cmp_ge_f32_e64 s[0:1], 0, v29
	v_add_u32_e32 v29, 1, v25
	s_nop 0
	v_cndmask_b32_e64 v28, v25, v28, s[0:1]
	v_fma_f32 v25, -v29, v25, v9
	v_cmp_lt_f32_e64 s[0:1], 0, v25
	s_nop 1
	v_cndmask_b32_e64 v25, v28, v29, s[0:1]
	v_mul_f32_e32 v28, 0x37800000, v25
	v_cndmask_b32_e32 v25, v25, v28, vcc
	v_cmp_class_f32_e32 vcc, v9, v149
	s_nop 1
	v_cndmask_b32_e32 v25, v25, v9, vcc
	v_pk_mul_f32 v[18:19], v[24:25], v[18:19]
	s_nop 0
	v_pk_fma_f32 v[16:17], v[16:17], v[26:27], v[18:19]
	s_waitcnt vmcnt(5)
	v_mov_b32_e32 v2, v104
	v_mov_b32_e32 v3, v105
	s_nop 0
	s_waitcnt vmcnt(4)
	v_mov_b32_e32 v18, v106
	v_mov_b32_e32 v19, v107
	s_nop 0
	v_and_b32_e32 v9, 0xffff0000, v2
	v_lshlrev_b32_e32 v2, 16, v2
	v_mul_f32_e32 v2, 0x3fb8aa3b, v2
	v_exp_f32_e32 v24, v2
	v_and_b32_e32 v28, 0xffff0000, v3
	v_lshlrev_b32_e32 v29, 16, v3
	s_nop 0
	v_and_b32_e32 v21, 0xffff0000, v18
	v_fma_f32 v2, -v24, v24, 1.0
	v_max_f32_e32 v2, 0, v2
	v_cmp_gt_f32_e32 vcc, s97, v2
	v_mul_f32_e32 v3, 0x4f800000, v2
	v_lshlrev_b32_e32 v20, 16, v18
	v_cndmask_b32_e32 v2, v2, v3, vcc
	v_sqrt_f32_e32 v3, v2
	v_lshlrev_b32_e32 v18, 16, v19
	v_and_b32_e32 v19, 0xffff0000, v19
	v_add_u32_e32 v25, -1, v3
	v_fma_f32 v26, -v25, v3, v2
	v_cmp_ge_f32_e64 s[0:1], 0, v26
	v_add_u32_e32 v26, 1, v3
	s_nop 0
	v_cndmask_b32_e64 v25, v3, v25, s[0:1]
	v_fma_f32 v3, -v26, v3, v2
	v_cmp_lt_f32_e64 s[0:1], 0, v3
	s_nop 1
	v_cndmask_b32_e64 v3, v25, v26, s[0:1]
	v_mul_f32_e32 v25, 0x37800000, v3
	v_cndmask_b32_e32 v3, v3, v25, vcc
	v_cmp_class_f32_e32 vcc, v2, v149
	s_nop 1
	v_cndmask_b32_e32 v26, v3, v2, vcc
	v_mul_f32_e32 v2, 0x3fb8aa3b, v9
	v_exp_f32_e32 v25, v2
	s_nop 0
	v_fma_f32 v2, -v25, v25, 1.0
	v_max_f32_e32 v2, 0, v2
	v_cmp_gt_f32_e32 vcc, s97, v2
	v_mul_f32_e32 v3, 0x4f800000, v2
	s_nop 0
	v_cndmask_b32_e32 v2, v2, v3, vcc
	v_sqrt_f32_e32 v3, v2
	s_nop 0
	v_add_u32_e32 v9, -1, v3
	v_fma_f32 v27, -v9, v3, v2
	v_cmp_ge_f32_e64 s[0:1], 0, v27
	v_add_u32_e32 v27, 1, v3
	s_nop 0
	v_cndmask_b32_e64 v9, v3, v9, s[0:1]
	v_fma_f32 v3, -v27, v3, v2
	v_cmp_lt_f32_e64 s[0:1], 0, v3
	s_nop 1
	v_cndmask_b32_e64 v3, v9, v27, s[0:1]
	v_mul_f32_e32 v9, 0x37800000, v3
	v_cndmask_b32_e32 v3, v3, v9, vcc
	v_cmp_class_f32_e32 vcc, v2, v149
	s_nop 1
	v_cndmask_b32_e32 v27, v3, v2, vcc
	v_pk_mul_f32 v[2:3], v[4:5], v[24:25]
	v_pk_mul_f32 v[4:5], v[26:27], v[20:21]
	s_nop 0
	v_pk_fma_f32 v[4:5], v[6:7], v[24:25], v[4:5]
	v_mul_f32_e32 v6, 0x3fb8aa3b, v29
	v_exp_f32_e32 v20, v6
	s_nop 0
	v_fma_f32 v6, -v20, v20, 1.0
	v_max_f32_e32 v6, 0, v6
	v_cmp_gt_f32_e32 vcc, s97, v6
	v_mul_f32_e32 v7, 0x4f800000, v6
	s_nop 0
	v_cndmask_b32_e32 v6, v6, v7, vcc
	v_sqrt_f32_e32 v7, v6
	s_nop 0
	v_add_u32_e32 v9, -1, v7
	v_fma_f32 v21, -v9, v7, v6
	v_cmp_ge_f32_e64 s[0:1], 0, v21
	v_add_u32_e32 v21, 1, v7
	s_nop 0
	v_cndmask_b32_e64 v9, v7, v9, s[0:1]
	v_fma_f32 v7, -v21, v7, v6
	v_cmp_lt_f32_e64 s[0:1], 0, v7
	s_nop 1
	v_cndmask_b32_e64 v7, v9, v21, s[0:1]
	v_mul_f32_e32 v9, 0x37800000, v7
	v_cndmask_b32_e32 v7, v7, v9, vcc
	v_cmp_class_f32_e32 vcc, v6, v149
	s_nop 1
	v_cndmask_b32_e32 v24, v7, v6, vcc
	v_mul_f32_e32 v6, 0x3fb8aa3b, v28
	v_exp_f32_e32 v21, v6
	s_nop 0
	v_fma_f32 v9, -v21, v21, 1.0
	v_max_f32_e32 v9, 0, v9
	v_pk_mul_f32 v[6:7], v[14:15], v[20:21]
	v_cmp_gt_f32_e32 vcc, s97, v9
	v_mul_f32_e32 v14, 0x4f800000, v9
	s_nop 0
	v_cndmask_b32_e32 v9, v9, v14, vcc
	v_sqrt_f32_e32 v14, v9
	s_nop 0
	v_add_u32_e32 v15, -1, v14
	v_fma_f32 v25, -v15, v14, v9
	v_cmp_ge_f32_e64 s[0:1], 0, v25
	v_add_u32_e32 v25, 1, v14
	s_nop 0
	v_cndmask_b32_e64 v15, v14, v15, s[0:1]
	v_fma_f32 v14, -v25, v14, v9
	v_cmp_lt_f32_e64 s[0:1], 0, v14
	s_nop 1
	v_cndmask_b32_e64 v14, v15, v25, s[0:1]
	v_mul_f32_e32 v15, 0x37800000, v14
	v_cndmask_b32_e32 v14, v14, v15, vcc
	v_cmp_class_f32_e32 vcc, v9, v149
	s_mov_b32 s0, 0x22cbc000
	s_nop 0
	v_cndmask_b32_e32 v25, v14, v9, vcc
	v_add_co_u32_e32 v12, vcc, s0, v12
	v_pk_mul_f32 v[14:15], v[24:25], v[18:19]
	s_nop 0
	v_addc_co_u32_e32 v13, vcc, 0, v13, vcc
	v_pk_fma_f32 v[14:15], v[16:17], v[20:21], v[14:15]
	s_waitcnt vmcnt(3)
	v_mov_b32_e32 v16, v108
	v_mov_b32_e32 v17, v109
	s_waitcnt vmcnt(2)
	v_mov_b32_e32 v18, v110
	v_mov_b32_e32 v19, v111
	s_nop 0
	v_and_b32_e32 v9, 0xffff0000, v16
	v_lshlrev_b32_e32 v16, 16, v16
	v_mul_f32_e32 v16, 0x3fb8aa3b, v16
	v_exp_f32_e32 v16, v16
	v_and_b32_e32 v26, 0xffff0000, v17
	v_lshlrev_b32_e32 v27, 16, v17
	v_mul_f32_e32 v9, 0x3fb8aa3b, v9
	v_fma_f32 v17, -v16, v16, 1.0
	v_max_f32_e32 v17, 0, v17
	v_cmp_gt_f32_e32 vcc, s97, v17
	v_mul_f32_e32 v24, 0x4f800000, v17
	s_nop 0
	v_and_b32_e32 v21, 0xffff0000, v18
	v_cndmask_b32_e32 v17, v17, v24, vcc
	v_sqrt_f32_e32 v24, v17
	v_lshlrev_b32_e32 v20, 16, v18
	v_lshlrev_b32_e32 v18, 16, v19
	v_and_b32_e32 v19, 0xffff0000, v19
	v_add_u32_e32 v25, -1, v24
	v_fma_f32 v28, -v25, v24, v17
	v_cmp_ge_f32_e64 s[0:1], 0, v28
	v_add_u32_e32 v28, 1, v24
	s_nop 0
	v_cndmask_b32_e64 v25, v24, v25, s[0:1]
	v_fma_f32 v24, -v28, v24, v17
	v_cmp_lt_f32_e64 s[0:1], 0, v24
	s_nop 1
	v_cndmask_b32_e64 v24, v25, v28, s[0:1]
	v_mul_f32_e32 v25, 0x37800000, v24
	v_cndmask_b32_e32 v24, v24, v25, vcc
	v_cmp_class_f32_e32 vcc, v17, v149
	s_nop 1
	v_cndmask_b32_e32 v24, v24, v17, vcc
	v_exp_f32_e32 v17, v9
	s_nop 0
	v_fma_f32 v9, -v17, v17, 1.0
	v_max_f32_e32 v9, 0, v9
	v_cmp_gt_f32_e32 vcc, s97, v9
	v_mul_f32_e32 v25, 0x4f800000, v9
	v_pk_mul_f32 v[2:3], v[2:3], v[16:17]
	v_cndmask_b32_e32 v9, v9, v25, vcc
	v_sqrt_f32_e32 v25, v9
	s_nop 0
	v_add_u32_e32 v28, -1, v25
	v_fma_f32 v29, -v28, v25, v9
	v_cmp_ge_f32_e64 s[0:1], 0, v29
	v_add_u32_e32 v29, 1, v25
	s_nop 0
	v_cndmask_b32_e64 v28, v25, v28, s[0:1]
	v_fma_f32 v25, -v29, v25, v9
	v_cmp_lt_f32_e64 s[0:1], 0, v25
	s_nop 1
	v_cndmask_b32_e64 v25, v28, v29, s[0:1]
	v_mul_f32_e32 v28, 0x37800000, v25
	v_cndmask_b32_e32 v25, v25, v28, vcc
	v_cmp_class_f32_e32 vcc, v9, v149
	s_nop 1
	v_cndmask_b32_e32 v25, v25, v9, vcc
	v_pk_mul_f32 v[20:21], v[24:25], v[20:21]
	s_nop 0
	v_pk_fma_f32 v[16:17], v[4:5], v[16:17], v[20:21]
	v_mul_f32_e32 v4, 0x3fb8aa3b, v27
	v_exp_f32_e32 v4, v4
	s_nop 0
	v_fma_f32 v5, -v4, v4, 1.0
	v_max_f32_e32 v5, 0, v5
	v_cmp_gt_f32_e32 vcc, s97, v5
	v_mul_f32_e32 v9, 0x4f800000, v5
	s_nop 0
	v_cndmask_b32_e32 v5, v5, v9, vcc
	v_sqrt_f32_e32 v9, v5
	s_nop 0
	v_add_u32_e32 v20, -1, v9
	v_fma_f32 v21, -v20, v9, v5
	v_cmp_ge_f32_e64 s[0:1], 0, v21
	v_add_u32_e32 v21, 1, v9
	s_nop 0
	v_cndmask_b32_e64 v20, v9, v20, s[0:1]
	v_fma_f32 v9, -v21, v9, v5
	v_cmp_lt_f32_e64 s[0:1], 0, v9
	s_nop 1
	v_cndmask_b32_e64 v9, v20, v21, s[0:1]
	v_mul_f32_e32 v20, 0x37800000, v9
	v_cndmask_b32_e32 v9, v9, v20, vcc
	v_cmp_class_f32_e32 vcc, v5, v149
	s_nop 1
	v_cndmask_b32_e32 v20, v9, v5, vcc
	v_mul_f32_e32 v5, 0x3fb8aa3b, v26
	v_exp_f32_e32 v5, v5
	s_nop 0
	v_fma_f32 v9, -v5, v5, 1.0
	v_max_f32_e32 v9, 0, v9
	v_cmp_gt_f32_e32 vcc, s97, v9
	v_mul_f32_e32 v21, 0x4f800000, v9
	v_pk_mul_f32 v[6:7], v[6:7], v[4:5]
	v_cndmask_b32_e32 v9, v9, v21, vcc
	v_sqrt_f32_e32 v21, v9
	s_nop 0
	v_add_u32_e32 v24, -1, v21
	v_fma_f32 v25, -v24, v21, v9
	v_cmp_ge_f32_e64 s[0:1], 0, v25
	v_add_u32_e32 v25, 1, v21
	s_nop 0
	v_cndmask_b32_e64 v24, v21, v24, s[0:1]
	v_fma_f32 v21, -v25, v21, v9
	v_cmp_lt_f32_e64 s[0:1], 0, v21
	s_nop 1
	v_cndmask_b32_e64 v21, v24, v25, s[0:1]
	v_mul_f32_e32 v24, 0x37800000, v21
	v_cndmask_b32_e32 v21, v21, v24, vcc
	v_cmp_class_f32_e32 vcc, v9, v149
	s_nop 1
	v_cndmask_b32_e32 v21, v21, v9, vcc
	v_pk_mul_f32 v[18:19], v[20:21], v[18:19]
	s_nop 0
	v_pk_fma_f32 v[14:15], v[14:15], v[4:5], v[18:19]
	s_waitcnt vmcnt(1)
	v_mov_b32_e32 v4, v112
	v_mov_b32_e32 v5, v113
	s_nop 0
	s_waitcnt vmcnt(0)
	v_mov_b32_e32 v12, v114
	v_mov_b32_e32 v13, v115
	s_nop 0
	v_and_b32_e32 v9, 0xffff0000, v4
	v_lshlrev_b32_e32 v4, 16, v4
	v_mul_f32_e32 v4, 0x3fb8aa3b, v4
	v_exp_f32_e32 v18, v4
	v_and_b32_e32 v24, 0xffff0000, v5
	v_lshlrev_b32_e32 v25, 16, v5
	s_nop 0
	v_and_b32_e32 v1, 0xffff0000, v12
	v_fma_f32 v4, -v18, v18, 1.0
	v_max_f32_e32 v4, 0, v4
	v_cmp_gt_f32_e32 vcc, s97, v4
	v_mul_f32_e32 v5, 0x4f800000, v4
	v_lshlrev_b32_e32 v0, 16, v12
	v_cndmask_b32_e32 v4, v4, v5, vcc
	v_sqrt_f32_e32 v5, v4
	v_lshlrev_b32_e32 v12, 16, v13
	v_and_b32_e32 v13, 0xffff0000, v13
	v_add_u32_e32 v19, -1, v5
	v_fma_f32 v20, -v19, v5, v4
	v_cmp_ge_f32_e64 s[0:1], 0, v20
	v_add_u32_e32 v20, 1, v5
	s_nop 0
	v_cndmask_b32_e64 v19, v5, v19, s[0:1]
	v_fma_f32 v5, -v20, v5, v4
	v_cmp_lt_f32_e64 s[0:1], 0, v5
	s_nop 1
	v_cndmask_b32_e64 v5, v19, v20, s[0:1]
	v_mul_f32_e32 v19, 0x37800000, v5
	v_cndmask_b32_e32 v5, v5, v19, vcc
	v_cmp_class_f32_e32 vcc, v4, v149
	s_nop 1
	v_cndmask_b32_e32 v20, v5, v4, vcc
	v_mul_f32_e32 v4, 0x3fb8aa3b, v9
	v_exp_f32_e32 v19, v4
	s_nop 0
	v_fma_f32 v4, -v19, v19, 1.0
	v_max_f32_e32 v4, 0, v4
	v_cmp_gt_f32_e32 vcc, s97, v4
	v_mul_f32_e32 v5, 0x4f800000, v4
	s_nop 0
	v_cndmask_b32_e32 v4, v4, v5, vcc
	v_sqrt_f32_e32 v5, v4
	s_nop 0
	v_add_u32_e32 v9, -1, v5
	v_fma_f32 v21, -v9, v5, v4
	v_cmp_ge_f32_e64 s[0:1], 0, v21
	v_add_u32_e32 v21, 1, v5
	s_nop 0
	v_cndmask_b32_e64 v9, v5, v9, s[0:1]
	v_fma_f32 v5, -v21, v5, v4
	v_cmp_lt_f32_e64 s[0:1], 0, v5
	s_nop 1
	v_cndmask_b32_e64 v5, v9, v21, s[0:1]
	v_mul_f32_e32 v9, 0x37800000, v5
	v_cndmask_b32_e32 v5, v5, v9, vcc
	v_cmp_class_f32_e32 vcc, v4, v149
	s_nop 1
	v_cndmask_b32_e32 v21, v5, v4, vcc
	v_pk_mul_f32 v[4:5], v[2:3], v[18:19]
	v_mul_f32_e32 v2, 0x3fb8aa3b, v25
	v_exp_f32_e32 v2, v2
	v_pk_mul_f32 v[0:1], v[20:21], v[0:1]
	v_fma_f32 v3, -v2, v2, 1.0
	v_max_f32_e32 v3, 0, v3
	v_cmp_gt_f32_e32 vcc, s97, v3
	v_mul_f32_e32 v9, 0x4f800000, v3
	v_pk_fma_f32 v[0:1], v[16:17], v[18:19], v[0:1]
	v_cndmask_b32_e32 v3, v3, v9, vcc
	v_sqrt_f32_e32 v9, v3
	s_nop 0
	v_add_u32_e32 v16, -1, v9
	v_fma_f32 v17, -v16, v9, v3
	v_cmp_ge_f32_e64 s[0:1], 0, v17
	v_add_u32_e32 v17, 1, v9
	s_nop 0
	v_cndmask_b32_e64 v16, v9, v16, s[0:1]
	v_fma_f32 v9, -v17, v9, v3
	v_cmp_lt_f32_e64 s[0:1], 0, v9
	s_nop 1
	v_cndmask_b32_e64 v9, v16, v17, s[0:1]
	v_mul_f32_e32 v16, 0x37800000, v9
	v_cndmask_b32_e32 v9, v9, v16, vcc
	v_cmp_class_f32_e32 vcc, v3, v149
	s_nop 1
	v_cndmask_b32_e32 v16, v9, v3, vcc
	v_mul_f32_e32 v3, 0x3fb8aa3b, v24
	v_exp_f32_e32 v3, v3
	s_nop 0
	v_fma_f32 v9, -v3, v3, 1.0
	v_max_f32_e32 v9, 0, v9
	v_cmp_gt_f32_e32 vcc, s97, v9
	v_mul_f32_e32 v17, 0x4f800000, v9
	v_pk_mul_f32 v[6:7], v[6:7], v[2:3]
	v_cndmask_b32_e32 v9, v9, v17, vcc
	v_sqrt_f32_e32 v17, v9
	s_nop 0
	v_add_u32_e32 v18, -1, v17
	v_fma_f32 v19, -v18, v17, v9
	v_cmp_ge_f32_e64 s[0:1], 0, v19
	v_add_u32_e32 v19, 1, v17
	s_nop 0
	v_cndmask_b32_e64 v18, v17, v18, s[0:1]
	v_fma_f32 v17, -v19, v17, v9
	v_cmp_lt_f32_e64 s[0:1], 0, v17
	s_nop 1
	v_cndmask_b32_e64 v17, v18, v19, s[0:1]
	v_mul_f32_e32 v18, 0x37800000, v17
	v_cndmask_b32_e32 v17, v17, v18, vcc
	v_cmp_class_f32_e32 vcc, v9, v149
	s_nop 1
	v_cndmask_b32_e32 v17, v17, v9, vcc
	v_pk_mul_f32 v[12:13], v[16:17], v[12:13]
	s_nop 0
	v_pk_fma_f32 v[2:3], v[14:15], v[2:3], v[12:13]
	s_cbranch_scc0 .LBB0_374
	v_and_b32_e32 v9, 63, v23
	v_lshl_or_b32 v8, v8, 6, v9
	v_ashrrev_i32_e32 v9, 31, v8
	v_lshlrev_b64 v[8:9], 13, v[8:9]
	v_lshlrev_b32_e32 v10, 4, v177
	v_lshl_add_u64 v[8:9], s[6:7], 0, v[8:9]
	v_and_b32_e32 v96, 0xff0, v10
	v_lshl_add_u64 v[8:9], v[8:9], 0, v[96:97]
	global_store_dwordx4 v[8:9], v[4:7], off
	v_add_u32_e32 v177, s2, v177
	s_mov_b32 s0, 0xffff
	v_add_co_u32_e32 v4, vcc, 0x1000, v8
	v_add_u32_e32 v22, s12, v22
	s_nop 0
	v_addc_co_u32_e32 v5, vcc, 0, v9, vcc
	v_cmp_lt_i32_e32 vcc, s0, v177
	s_or_b64 s[8:9], vcc, s[8:9]
	global_store_dwordx4 v[4:5], v[0:3], off
	s_andn2_b64 exec, exec, s[8:9]
	s_cbranch_execnz .LBB0_373
